# resid epilogue store ladder de-serialised (counted vmcnt) + hand-scheduled swiglu epilogue with dwordx4 stores via permlane16_swap
# speedup vs baseline: 1.0274x; 1.0274x over previous
; #define PG8_STAGE(bufoff, gbase, voff) do { _Pragma("unroll") for (int _i = 0; _i < 2; ++_i) \
;     __builtin_amdgcn_global_load_lds((const unsigned*)((const char*)(gbase) + (voff)[_i]), (PG8_LAS unsigned*)(lds + (bufoff) + ldsw + _i * 8192), 16, 0, 0); } while (0)
; #define PG8_LDA(dst, b, h) do { _Pragma("unroll") for (int m = 0; m < 4; ++m) _Pragma("unroll") for (int k = 0; k < 2; ++k) dst[m][k] = *(const PG8_LAS bf16x8*)(lds + PG8_SA(b, h) + aoff + m * 2048 + k * 1024); } while (0)
; #define PG8_LDB(dst, b, h) do { _Pragma("unroll") for (int n = 0; n < 2; ++n) _Pragma("unroll") for (int k = 0; k < 2; ++k) dst[n][k] = *(const PG8_LAS bf16x8*)(lds + PG8_SB(b, h) + boff + n * 2048 + k * 1024); } while (0)
; #define PG8_MMA(ai, bj, At, Bt) do { __builtin_amdgcn_s_setprio(1); _Pragma("unroll") for (int m = 0; m < 4; ++m) _Pragma("unroll") for (int n = 0; n < 2; ++n) _Pragma("unroll") for (int k = 0; k < 2; ++k) \
;     acc[ai][bj][m][n] = __builtin_amdgcn_mfma_f32_16x16x32_bf16(Bt[n][k], At[m][k], acc[ai][bj][m][n], 0, 0, 0); __builtin_amdgcn_s_setprio(0); } while (0)
; #define PG8_WAIT_L(n) asm volatile("s_waitcnt lgkmcnt(" #n ")" ::: "memory")
; #define PG8_BAR __builtin_amdgcn_s_barrier()
; #define PG8_SCHED __builtin_amdgcn_sched_barrier(0)
; template <class Epi>
; DI void gemm_phase(PG8_LAS unsigned char* lds, const Gemm g, const StaticOrder& S, const Epi& E) {
;     ...
;       PG8_LDB(B0, 0, 0); PG8_SCHED; PG8_LDA(At, 0, 0); PG8_STAGE(PG8_SA(1, 1), a1 + hstepA, voffA);
;       PG8_WAIT_L(8); PG8_BAR; PG8_WAIT_L(0); PG8_MMA(0, 0, At, B0); PG8_BAR; PG8_SCHED;
;       PG8_LDB(B1, 0, 1); PG8_STAGE(PG8_SB(0, 0), b2, voffB);
;       PG8_BAR; PG8_WAIT_L(0); PG8_MMA(0, 1, At, B1); PG8_BAR;
;       PG8_LDA(At, 0, 1); PG8_STAGE(PG8_SA(0, 0), a2, voffA);
;       PG8_BAR; PG8_WAIT_L(0); PG8_MMA(1, 0, At, B0); PG8_BAR; PG8_SCHED;
.LBB0_52:
	s_add_u32 s58, s56, 0xfffc0080
	s_addc_u32 s59, s57, -1
	s_add_i32 s77, 0, 0x10000
	v_add_u32_e32 v153, s77, v149
	ds_read_b128 v[144:147], v153
	ds_read_b128 v[154:157], v153 offset:1024
	ds_read_b128 v[158:161], v153 offset:2048
	ds_read_b128 v[162:165], v153 offset:3072
	s_cmp_eq_u32 s76, 12
	s_cselect_b32 s61, s51, s59
	s_cselect_b32 s60, s72, s58
	s_cselect_b32 s59, s31, s75
	s_cselect_b32 s58, s73, s74
	v_lshl_add_u64 v[198:199], s[56:57], 0, v[132:133]
	s_add_i32 m0, s37, 0xc000
	ds_read_b128 v[166:169], v152
	ds_read_b128 v[170:173], v152 offset:1024
	ds_read_b128 v[174:177], v152 offset:2048
	ds_read_b128 v[178:181], v152 offset:3072
	ds_read_b128 v[182:185], v152 offset:4096
	ds_read_b128 v[186:189], v152 offset:5120
	ds_read_b128 v[190:193], v152 offset:6144
	ds_read_b128 v[194:197], v152 offset:7168
	global_load_lds_dwordx4 v[198:199], off
	v_lshl_add_u64 v[198:199], s[56:57], 0, v[142:143]
	s_add_i32 m0, s37, 0xe000
	s_nop 0
	global_load_lds_dwordx4 v[198:199], off
	s_waitcnt lgkmcnt(8)
	s_barrier
	s_waitcnt lgkmcnt(0)
	s_setprio 1
	s_waitcnt lgkmcnt(0)
	v_mfma_f32_16x16x32_bf16 v[126:129], v[144:147], v[166:169], v[126:129]
	v_mfma_f32_16x16x32_bf16 v[122:125], v[158:161], v[166:169], v[122:125]
	v_mfma_f32_16x16x32_bf16 v[110:113], v[144:147], v[174:177], v[110:113]
	v_mfma_f32_16x16x32_bf16 v[106:109], v[158:161], v[174:177], v[106:109]
	v_mfma_f32_16x16x32_bf16 v[94:97], v[144:147], v[182:185], v[94:97]
	v_mfma_f32_16x16x32_bf16 v[90:93], v[158:161], v[182:185], v[90:93]
	v_mfma_f32_16x16x32_bf16 v[78:81], v[144:147], v[190:193], v[78:81]
	v_mfma_f32_16x16x32_bf16 v[74:77], v[158:161], v[190:193], v[74:77]
	v_mfma_f32_16x16x32_bf16 v[126:129], v[154:157], v[170:173], v[126:129]
	v_mfma_f32_16x16x32_bf16 v[122:125], v[162:165], v[170:173], v[122:125]
	v_mfma_f32_16x16x32_bf16 v[110:113], v[154:157], v[178:181], v[110:113]
	v_mfma_f32_16x16x32_bf16 v[106:109], v[162:165], v[178:181], v[106:109]
	v_mfma_f32_16x16x32_bf16 v[94:97], v[154:157], v[186:189], v[94:97]
	v_mfma_f32_16x16x32_bf16 v[90:93], v[162:165], v[186:189], v[90:93]
	v_mfma_f32_16x16x32_bf16 v[78:81], v[154:157], v[194:197], v[78:81]
	v_mfma_f32_16x16x32_bf16 v[74:77], v[162:165], v[194:197], v[74:77]
	s_setprio 0
	s_barrier
	s_add_i32 s80, 0, 0x14000
	s_add_i32 s77, s77, s34
	v_add_u32_e32 v153, s80, v149
	v_lshl_add_u64 v[198:199], s[58:59], 0, v[0:1]
	s_mov_b32 m0, s77
	ds_read_b128 v[222:225], v153
	ds_read_b128 v[226:229], v153 offset:1024
	ds_read_b128 v[230:233], v153 offset:2048
	ds_read_b128 v[234:237], v153 offset:3072
	global_load_lds_dwordx4 v[198:199], off
	v_lshl_add_u64 v[238:239], s[58:59], 0, v[130:131]
	s_add_i32 m0, s77, 0x2000
	s_nop 0
	global_load_lds_dwordx4 v[238:239], off
	s_barrier
	s_waitcnt lgkmcnt(0)
	s_setprio 1
	s_waitcnt lgkmcnt(0)
	v_mfma_f32_16x16x32_bf16 v[118:121], v[222:225], v[166:169], v[118:121]
	v_mfma_f32_16x16x32_bf16 v[114:117], v[230:233], v[166:169], v[114:117]
	v_mfma_f32_16x16x32_bf16 v[102:105], v[222:225], v[174:177], v[102:105]
	v_mfma_f32_16x16x32_bf16 v[98:101], v[230:233], v[174:177], v[98:101]
	v_mfma_f32_16x16x32_bf16 v[86:89], v[222:225], v[182:185], v[86:89]
	v_mfma_f32_16x16x32_bf16 v[82:85], v[230:233], v[182:185], v[82:85]
	v_mfma_f32_16x16x32_bf16 v[70:73], v[222:225], v[190:193], v[70:73]
	v_mfma_f32_16x16x32_bf16 v[66:69], v[230:233], v[190:193], v[66:69]
	v_mfma_f32_16x16x32_bf16 v[118:121], v[226:229], v[170:173], v[118:121]
	v_mfma_f32_16x16x32_bf16 v[114:117], v[234:237], v[170:173], v[114:117]
	v_mfma_f32_16x16x32_bf16 v[102:105], v[226:229], v[178:181], v[102:105]
	v_mfma_f32_16x16x32_bf16 v[98:101], v[234:237], v[178:181], v[98:101]
	v_mfma_f32_16x16x32_bf16 v[86:89], v[226:229], v[186:189], v[86:89]
	v_mfma_f32_16x16x32_bf16 v[82:85], v[234:237], v[186:189], v[82:85]
	v_mfma_f32_16x16x32_bf16 v[70:73], v[226:229], v[194:197], v[70:73]
	v_mfma_f32_16x16x32_bf16 v[66:69], v[234:237], v[194:197], v[66:69]
	s_setprio 0
	s_mov_b32 m0, s37
	v_lshl_add_u64 v[240:241], s[60:61], 0, v[0:1]
	s_barrier
	ds_read_b128 v[166:169], v152 offset:16384
	ds_read_b128 v[170:173], v152 offset:17408
	ds_read_b128 v[174:177], v152 offset:18432
	ds_read_b128 v[178:181], v152 offset:19456
	ds_read_b128 v[182:185], v152 offset:20480
	ds_read_b128 v[186:189], v152 offset:21504
	ds_read_b128 v[190:193], v152 offset:22528
	ds_read_b128 v[194:197], v152 offset:23552
	global_load_lds_dwordx4 v[240:241], off
	v_lshl_add_u64 v[242:243], s[60:61], 0, v[130:131]
	s_mov_b32 m0, s62
	s_nop 0
	global_load_lds_dwordx4 v[242:243], off
	s_barrier
	s_waitcnt lgkmcnt(0)
	s_setprio 1
	s_waitcnt lgkmcnt(0)
	v_mfma_f32_16x16x32_bf16 v[62:65], v[144:147], v[166:169], v[62:65]
	v_mfma_f32_16x16x32_bf16 v[58:61], v[158:161], v[166:169], v[58:61]
	v_mfma_f32_16x16x32_bf16 v[46:49], v[144:147], v[174:177], v[46:49]
	v_mfma_f32_16x16x32_bf16 v[42:45], v[158:161], v[174:177], v[42:45]
	v_mfma_f32_16x16x32_bf16 v[30:33], v[144:147], v[182:185], v[30:33]
	v_mfma_f32_16x16x32_bf16 v[26:29], v[158:161], v[182:185], v[26:29]
	v_mfma_f32_16x16x32_bf16 v[14:17], v[144:147], v[190:193], v[14:17]
	v_mfma_f32_16x16x32_bf16 v[10:13], v[158:161], v[190:193], v[10:13]
	v_mfma_f32_16x16x32_bf16 v[62:65], v[154:157], v[170:173], v[62:65]
	v_mfma_f32_16x16x32_bf16 v[58:61], v[162:165], v[170:173], v[58:61]
	v_mfma_f32_16x16x32_bf16 v[46:49], v[154:157], v[178:181], v[46:49]
	v_mfma_f32_16x16x32_bf16 v[42:45], v[162:165], v[178:181], v[42:45]
	v_mfma_f32_16x16x32_bf16 v[30:33], v[154:157], v[186:189], v[30:33]
	v_mfma_f32_16x16x32_bf16 v[26:29], v[162:165], v[186:189], v[26:29]
	v_mfma_f32_16x16x32_bf16 v[14:17], v[154:157], v[194:197], v[14:17]
	v_mfma_f32_16x16x32_bf16 v[10:13], v[162:165], v[194:197], v[10:13]
	s_setprio 0
	s_barrier
; #define PG8_STAGE(bufoff, gbase, voff) do { _Pragma("unroll") for (int _i = 0; _i < 2; ++_i) \
;     __builtin_amdgcn_global_load_lds((const unsigned*)((const char*)(gbase) + (voff)[_i]), (PG8_LAS unsigned*)(lds + (bufoff) + ldsw + _i * 8192), 16, 0, 0); } while (0)
; #define PG8_LDA(dst, b, h) do { _Pragma("unroll") for (int m = 0; m < 4; ++m) _Pragma("unroll") for (int k = 0; k < 2; ++k) dst[m][k] = *(const PG8_LAS bf16x8*)(lds + PG8_SA(b, h) + aoff + m * 2048 + k * 1024); } while (0)
; #define PG8_LDB(dst, b, h) do { _Pragma("unroll") for (int n = 0; n < 2; ++n) _Pragma("unroll") for (int k = 0; k < 2; ++k) dst[n][k] = *(const PG8_LAS bf16x8*)(lds + PG8_SB(b, h) + boff + n * 2048 + k * 1024); } while (0)
; #define PG8_MMA(ai, bj, At, Bt) do { __builtin_amdgcn_s_setprio(1); _Pragma("unroll") for (int m = 0; m < 4; ++m) _Pragma("unroll") for (int n = 0; n < 2; ++n) _Pragma("unroll") for (int k = 0; k < 2; ++k) \
;     acc[ai][bj][m][n] = __builtin_amdgcn_mfma_f32_16x16x32_bf16(Bt[n][k], At[m][k], acc[ai][bj][m][n], 0, 0, 0); __builtin_amdgcn_s_setprio(0); } while (0)
; #define PG8_WAIT_V(n) asm volatile("s_waitcnt vmcnt(" #n ")" ::: "memory")
; #define PG8_WAIT_L(n) asm volatile("s_waitcnt lgkmcnt(" #n ")" ::: "memory")
; #define PG8_BAR __builtin_amdgcn_s_barrier()
; #define PG8_SCHED __builtin_amdgcn_sched_barrier(0)
; template <class Epi>
; DI void gemm_phase(PG8_LAS unsigned char* lds, const Gemm g, const StaticOrder& S, const Epi& E) {
;     ...
;       PG8_STAGE(PG8_SB(0, 1), b2 + hstepB, voffB);
;       PG8_WAIT_V(6); PG8_BAR; PG8_MMA(1, 1, At, B1); PG8_BAR;
;       PG8_LDB(B0, 1, 0); PG8_SCHED; PG8_LDA(At, 1, 0); PG8_STAGE(PG8_SA(0, 1), a2 + hstepA, voffA);
;       PG8_WAIT_L(8); PG8_BAR; PG8_WAIT_L(0); PG8_MMA(0, 0, At, B0); PG8_BAR; PG8_SCHED;
;       PG8_LDB(B1, 1, 1); PG8_STAGE(PG8_SB(1, 0), b3, voffB);
;       PG8_BAR; PG8_WAIT_L(0); PG8_MMA(0, 1, At, B1); PG8_BAR;
;       PG8_LDA(At, 1, 1); PG8_STAGE(PG8_SA(1, 0), a3, voffA);
	s_add_u32 s78, s58, 0x40000
	s_addc_u32 s79, s59, 0
	s_add_i32 s77, s80, s34
	v_lshl_add_u64 v[144:145], s[78:79], 0, v[0:1]
	s_mov_b32 m0, s77
	s_nop 0
	global_load_lds_dwordx4 v[144:145], off
	v_lshl_add_u64 v[144:145], s[78:79], 0, v[130:131]
	s_add_i32 m0, s77, 0x2000
	s_nop 0
	global_load_lds_dwordx4 v[144:145], off
	s_waitcnt vmcnt(6)
	s_barrier
	s_setprio 1
	v_mfma_f32_16x16x32_bf16 v[54:57], v[222:225], v[166:169], v[54:57]
	v_mfma_f32_16x16x32_bf16 v[50:53], v[230:233], v[166:169], v[50:53]
	v_mfma_f32_16x16x32_bf16 v[38:41], v[222:225], v[174:177], v[38:41]
	v_mfma_f32_16x16x32_bf16 v[34:37], v[230:233], v[174:177], v[34:37]
	v_mfma_f32_16x16x32_bf16 v[22:25], v[222:225], v[182:185], v[22:25]
	v_mfma_f32_16x16x32_bf16 v[18:21], v[230:233], v[182:185], v[18:21]
	v_mfma_f32_16x16x32_bf16 v[6:9], v[222:225], v[190:193], v[6:9]
	v_mfma_f32_16x16x32_bf16 v[2:5], v[230:233], v[190:193], v[2:5]
	v_mfma_f32_16x16x32_bf16 v[54:57], v[226:229], v[170:173], v[54:57]
	v_mfma_f32_16x16x32_bf16 v[50:53], v[234:237], v[170:173], v[50:53]
	v_mfma_f32_16x16x32_bf16 v[38:41], v[226:229], v[178:181], v[38:41]
	v_mfma_f32_16x16x32_bf16 v[34:37], v[234:237], v[178:181], v[34:37]
	v_mfma_f32_16x16x32_bf16 v[22:25], v[226:229], v[186:189], v[22:25]
	v_mfma_f32_16x16x32_bf16 v[18:21], v[234:237], v[186:189], v[18:21]
	v_mfma_f32_16x16x32_bf16 v[6:9], v[226:229], v[194:197], v[6:9]
	v_mfma_f32_16x16x32_bf16 v[2:5], v[234:237], v[194:197], v[2:5]
	s_setprio 0
	s_add_i32 s77, 0, 0x18000
	v_add_u32_e32 v153, s77, v149
	s_barrier
	ds_read_b128 v[144:147], v153
	ds_read_b128 v[154:157], v153 offset:1024
	ds_read_b128 v[158:161], v153 offset:2048
	ds_read_b128 v[162:165], v153 offset:3072
	s_add_u32 s60, s60, 0x40000
	s_addc_u32 s61, s61, 0
	s_mov_b32 m0, s63
	v_lshl_add_u64 v[222:223], s[60:61], 0, v[0:1]
	ds_read_b128 v[166:169], v152 offset:32768
	ds_read_b128 v[170:173], v152 offset:33792
	ds_read_b128 v[174:177], v152 offset:34816
	ds_read_b128 v[178:181], v152 offset:35840
	ds_read_b128 v[182:185], v152 offset:36864
	ds_read_b128 v[186:189], v152 offset:37888
	ds_read_b128 v[190:193], v152 offset:38912
	ds_read_b128 v[194:197], v152 offset:39936
	global_load_lds_dwordx4 v[222:223], off
	v_lshl_add_u64 v[222:223], s[60:61], 0, v[130:131]
	s_mov_b32 m0, s64
	s_nop 0
	global_load_lds_dwordx4 v[222:223], off
	s_waitcnt lgkmcnt(8)
	s_barrier
	s_waitcnt lgkmcnt(0)
	s_setprio 1
	s_waitcnt lgkmcnt(0)
	v_mfma_f32_16x16x32_bf16 v[126:129], v[144:147], v[166:169], v[126:129]
	v_mfma_f32_16x16x32_bf16 v[122:125], v[158:161], v[166:169], v[122:125]
	v_mfma_f32_16x16x32_bf16 v[110:113], v[144:147], v[174:177], v[110:113]
	v_mfma_f32_16x16x32_bf16 v[106:109], v[158:161], v[174:177], v[106:109]
	v_mfma_f32_16x16x32_bf16 v[94:97], v[144:147], v[182:185], v[94:97]
	v_mfma_f32_16x16x32_bf16 v[90:93], v[158:161], v[182:185], v[90:93]
	v_mfma_f32_16x16x32_bf16 v[78:81], v[144:147], v[190:193], v[78:81]
	v_mfma_f32_16x16x32_bf16 v[74:77], v[158:161], v[190:193], v[74:77]
	v_mfma_f32_16x16x32_bf16 v[126:129], v[154:157], v[170:173], v[126:129]
	v_mfma_f32_16x16x32_bf16 v[122:125], v[162:165], v[170:173], v[122:125]
	v_mfma_f32_16x16x32_bf16 v[110:113], v[154:157], v[178:181], v[110:113]
	v_mfma_f32_16x16x32_bf16 v[106:109], v[162:165], v[178:181], v[106:109]
	v_mfma_f32_16x16x32_bf16 v[94:97], v[154:157], v[186:189], v[94:97]
	v_mfma_f32_16x16x32_bf16 v[90:93], v[162:165], v[186:189], v[90:93]
	v_mfma_f32_16x16x32_bf16 v[78:81], v[154:157], v[194:197], v[78:81]
	v_mfma_f32_16x16x32_bf16 v[74:77], v[162:165], v[194:197], v[74:77]
	s_setprio 0
	s_barrier
	s_add_i32 s60, 0, 0x1c000
	s_add_i32 s61, s77, s34
	v_add_u32_e32 v153, s60, v149
	v_lshl_add_u64 v[198:199], v[198:199], 0, s[86:87]
	s_mov_b32 m0, s61
	ds_read_b128 v[222:225], v153
	ds_read_b128 v[226:229], v153 offset:1024
	ds_read_b128 v[230:233], v153 offset:2048
	ds_read_b128 v[234:237], v153 offset:3072
	global_load_lds_dwordx4 v[198:199], off
	v_lshl_add_u64 v[198:199], v[238:239], 0, s[86:87]
	s_add_i32 m0, s61, 0x2000
	s_nop 0
	global_load_lds_dwordx4 v[198:199], off
	s_barrier
	s_waitcnt lgkmcnt(0)
	s_setprio 1
	s_waitcnt lgkmcnt(0)
	v_mfma_f32_16x16x32_bf16 v[118:121], v[222:225], v[166:169], v[118:121]
	v_mfma_f32_16x16x32_bf16 v[114:117], v[230:233], v[166:169], v[114:117]
	v_mfma_f32_16x16x32_bf16 v[102:105], v[222:225], v[174:177], v[102:105]
	v_mfma_f32_16x16x32_bf16 v[98:101], v[230:233], v[174:177], v[98:101]
	v_mfma_f32_16x16x32_bf16 v[86:89], v[222:225], v[182:185], v[86:89]
	v_mfma_f32_16x16x32_bf16 v[82:85], v[230:233], v[182:185], v[82:85]
	v_mfma_f32_16x16x32_bf16 v[70:73], v[222:225], v[190:193], v[70:73]
	v_mfma_f32_16x16x32_bf16 v[66:69], v[230:233], v[190:193], v[66:69]
	v_mfma_f32_16x16x32_bf16 v[118:121], v[226:229], v[170:173], v[118:121]
	v_mfma_f32_16x16x32_bf16 v[114:117], v[234:237], v[170:173], v[114:117]
	v_mfma_f32_16x16x32_bf16 v[102:105], v[226:229], v[178:181], v[102:105]
	v_mfma_f32_16x16x32_bf16 v[98:101], v[234:237], v[178:181], v[98:101]
	v_mfma_f32_16x16x32_bf16 v[86:89], v[226:229], v[186:189], v[86:89]
	v_mfma_f32_16x16x32_bf16 v[82:85], v[234:237], v[186:189], v[82:85]
	v_mfma_f32_16x16x32_bf16 v[70:73], v[226:229], v[194:197], v[70:73]
	v_mfma_f32_16x16x32_bf16 v[66:69], v[234:237], v[194:197], v[66:69]
	s_setprio 0
	s_mov_b32 m0, s65
	v_lshl_add_u64 v[198:199], v[240:241], 0, s[86:87]
	s_barrier
	ds_read_b128 v[166:169], v152 offset:49152
	ds_read_b128 v[170:173], v152 offset:50176
	ds_read_b128 v[174:177], v152 offset:51200
	ds_read_b128 v[178:181], v152 offset:52224
	ds_read_b128 v[182:185], v152 offset:53248
	ds_read_b128 v[186:189], v152 offset:54272
	ds_read_b128 v[190:193], v152 offset:55296
	ds_read_b128 v[194:197], v152 offset:56320
	global_load_lds_dwordx4 v[198:199], off
	v_lshl_add_u64 v[198:199], v[242:243], 0, s[86:87]
	s_mov_b32 m0, s66
	s_nop 0
	global_load_lds_dwordx4 v[198:199], off
	s_barrier
; DI unsigned pk2(float lo, float hi) { f32x2 v = {lo, hi}; bf2_t r = __builtin_convertvector(v, bf2_t); return __builtin_bit_cast(unsigned, r); }
; DI float silu(float x) { return x * __builtin_amdgcn_rcpf(1.f + __expf(-x)); }
; #define PG8_LAS __attribute__((address_space(3)))
; #define PG8_STAGE(bufoff, gbase, voff) do { _Pragma("unroll") for (int _i = 0; _i < 2; ++_i) \
;     __builtin_amdgcn_global_load_lds((const unsigned*)((const char*)(gbase) + (voff)[_i]), (PG8_LAS unsigned*)(lds + (bufoff) + ldsw + _i * 8192), 16, 0, 0); } while (0)
; #define PG8_MMA(ai, bj, At, Bt) do { __builtin_amdgcn_s_setprio(1); _Pragma("unroll") for (int m = 0; m < 4; ++m) _Pragma("unroll") for (int n = 0; n < 2; ++n) _Pragma("unroll") for (int k = 0; k < 2; ++k) \
;     acc[ai][bj][m][n] = __builtin_amdgcn_mfma_f32_16x16x32_bf16(Bt[n][k], At[m][k], acc[ai][bj][m][n], 0, 0, 0); __builtin_amdgcn_s_setprio(0); } while (0)
; #define PG8_WAIT_V(n) asm volatile("s_waitcnt vmcnt(" #n ")" ::: "memory")
; #define PG8_WAIT_L(n) asm volatile("s_waitcnt lgkmcnt(" #n ")" ::: "memory")
; #define PG8_BAR __builtin_amdgcn_s_barrier()
; #define PG8_SCHED __builtin_amdgcn_sched_barrier(0)
;   DI void operator()(const f32x4 (&acc)[2][2][4][2], const Unit& u, int wr, int wc, int fr, int fq, const PG8_LAS float* sR) const {
;     const int row0 = u.pm * BM + wr * 64 + fr, j0 = (u.pn * BM + wc * 32) / 2 + 4 * fq;
; #pragma unroll
;     for (int ai = 0; ai < 2; ++ai)
; #pragma unroll
;       for (int m = 0; m < 4; ++m) {
;         bf16_t* rowp = Hd + (size_t)(row0 + ai * HALF + m * 16) * 2816 + j0;
;         const float rs = sR[ai * 128 + m * 16 + fr];
; #pragma unroll
;         for (int bj = 0; bj < 2; ++bj) {
;           const f32x4 g = acc[ai][bj][m][0] * rs, up = acc[ai][bj][m][1] * rs;
;           u32x2 o; o[0] = pk2(silu(g[0]) * up[0], silu(g[1]) * up[1]); o[1] = pk2(silu(g[2]) * up[2], silu(g[3]) * up[3]);
;           *(u32x2*)(rowp + bj * (HALF / 2)) = o;
;         }
;       }
; template <class Epi>
; DI void gemm_phase(PG8_LAS unsigned char* lds, const Gemm g, const StaticOrder& S, const Epi& E) {
;     ...
;       PG8_BAR; PG8_WAIT_L(0); PG8_MMA(1, 0, At, B0); PG8_BAR; PG8_SCHED;
;       PG8_STAGE(PG8_SB(1, 1), b3 + hstepB, voffB);
;       PG8_WAIT_V(6); PG8_BAR; PG8_MMA(1, 1, At, B1); PG8_BAR;
	s_waitcnt lgkmcnt(0)
	s_setprio 1
	s_waitcnt lgkmcnt(0)
	v_mfma_f32_16x16x32_bf16 v[62:65], v[144:147], v[166:169], v[62:65]
	v_mfma_f32_16x16x32_bf16 v[58:61], v[158:161], v[166:169], v[58:61]
	v_mfma_f32_16x16x32_bf16 v[46:49], v[144:147], v[174:177], v[46:49]
	v_mfma_f32_16x16x32_bf16 v[42:45], v[158:161], v[174:177], v[42:45]
	v_mfma_f32_16x16x32_bf16 v[30:33], v[144:147], v[182:185], v[30:33]
	v_mfma_f32_16x16x32_bf16 v[26:29], v[158:161], v[182:185], v[26:29]
	v_mfma_f32_16x16x32_bf16 v[14:17], v[144:147], v[190:193], v[14:17]
	v_mfma_f32_16x16x32_bf16 v[10:13], v[158:161], v[190:193], v[10:13]
	v_mfma_f32_16x16x32_bf16 v[62:65], v[154:157], v[170:173], v[62:65]
	v_mfma_f32_16x16x32_bf16 v[58:61], v[162:165], v[170:173], v[58:61]
	v_mfma_f32_16x16x32_bf16 v[46:49], v[154:157], v[178:181], v[46:49]
	v_mfma_f32_16x16x32_bf16 v[42:45], v[162:165], v[178:181], v[42:45]
	v_mfma_f32_16x16x32_bf16 v[30:33], v[154:157], v[186:189], v[30:33]
	v_mfma_f32_16x16x32_bf16 v[26:29], v[162:165], v[186:189], v[26:29]
	v_mfma_f32_16x16x32_bf16 v[14:17], v[154:157], v[194:197], v[14:17]
	v_mfma_f32_16x16x32_bf16 v[10:13], v[162:165], v[194:197], v[10:13]
	s_setprio 0
	s_barrier
	s_add_u32 s58, s58, 0x40080
	s_addc_u32 s59, s59, 0
	s_add_i32 s60, s60, s34
	v_lshl_add_u64 v[144:145], s[58:59], 0, v[0:1]
	s_mov_b32 m0, s60
	s_nop 0
	global_load_lds_dwordx4 v[144:145], off
	v_lshl_add_u64 v[144:145], s[58:59], 0, v[130:131]
	s_add_i32 m0, s60, 0x2000
	s_nop 0
	global_load_lds_dwordx4 v[144:145], off
	s_waitcnt vmcnt(6)
	s_barrier
	s_setprio 1
	v_mfma_f32_16x16x32_bf16 v[54:57], v[222:225], v[166:169], v[54:57]
	v_mfma_f32_16x16x32_bf16 v[50:53], v[230:233], v[166:169], v[50:53]
	v_mfma_f32_16x16x32_bf16 v[38:41], v[222:225], v[174:177], v[38:41]
	v_mfma_f32_16x16x32_bf16 v[34:37], v[230:233], v[174:177], v[34:37]
	v_mfma_f32_16x16x32_bf16 v[22:25], v[222:225], v[182:185], v[22:25]
	v_mfma_f32_16x16x32_bf16 v[18:21], v[230:233], v[182:185], v[18:21]
	v_mfma_f32_16x16x32_bf16 v[6:9], v[222:225], v[190:193], v[6:9]
	v_mfma_f32_16x16x32_bf16 v[2:5], v[230:233], v[190:193], v[2:5]
	v_mfma_f32_16x16x32_bf16 v[54:57], v[226:229], v[170:173], v[54:57]
	v_mfma_f32_16x16x32_bf16 v[50:53], v[234:237], v[170:173], v[50:53]
	v_mfma_f32_16x16x32_bf16 v[38:41], v[226:229], v[178:181], v[38:41]
	v_mfma_f32_16x16x32_bf16 v[34:37], v[234:237], v[178:181], v[34:37]
	v_mfma_f32_16x16x32_bf16 v[22:25], v[226:229], v[186:189], v[22:25]
	v_mfma_f32_16x16x32_bf16 v[18:21], v[234:237], v[186:189], v[18:21]
	v_mfma_f32_16x16x32_bf16 v[6:9], v[226:229], v[194:197], v[6:9]
	v_mfma_f32_16x16x32_bf16 v[2:5], v[234:237], v[194:197], v[2:5]
	s_setprio 0
	s_add_i32 s76, s76, 2
	s_add_u32 s56, s56, 0x100
	s_addc_u32 s57, s57, 0
	s_add_u32 s74, s74, 0x100
	s_addc_u32 s75, s75, 0
	s_cmp_gt_u32 s76, 13
	s_barrier
	s_cbranch_scc0 .LBB0_52
	v_lshl_add_u32 v154, s69, 10, v150
	ds_read2_b32 v[158:159], v154 offset1:16
	ds_read2_b32 v[160:161], v154 offset0:32 offset1:48
	s_lshl_b32 s31, s70, 8
	s_or_b32 s31, s31, s67
	s_ashr_i32 s31, s31, 1
	v_readlane_b32 s18, v253, 30
	v_readlane_b32 s19, v253, 31
	v_or_b32_e32 v146, s31, v151
	v_lshl_add_u32 v153, s71, 8, v148
	v_ashrrev_i32_e32 v147, 31, v146
	s_movk_i32 s4, 0x1600
	v_mov_b64_e32 v[144:145], s[18:19]
	v_lshlrev_b64 v[146:147], 1, v[146:147]
	v_mad_i64_i32 v[156:157], s[56:57], v153, s4, v[144:145]
	v_and_b32_e32 v144, 4, v151
	v_mul_u32_u24_e32 v144, 30, v144
	v_mov_b32_e32 v145, 0
	v_lshl_add_u64 v[156:157], v[156:157], 0, v[146:147]
	s_mov_b32 s70, s30
	s_mov_b32 s71, s50
	s_mov_b64 s[58:59], s[54:55]
	v_lshl_add_u64 v[156:157], v[156:157], 0, v[144:145]
	v_readlane_b32 s5, v253, 17
	v_readlane_b32 s6, v253, 18
	v_readlane_b32 s7, v253, 19
	v_readlane_b32 s8, v253, 20
	v_readlane_b32 s9, v253, 21
	v_readlane_b32 s10, v253, 22
	v_readlane_b32 s11, v253, 23
	v_readlane_b32 s12, v253, 24
	v_readlane_b32 s13, v253, 25
	v_readlane_b32 s14, v253, 26
	v_readlane_b32 s15, v253, 27
	v_readlane_b32 s16, v253, 28
	v_readlane_b32 s17, v253, 29
	s_mov_b32 s56, 0x16000
	s_mov_b32 s57, 0
	s_waitcnt lgkmcnt(0)
	v_pk_mul_f32 v[126:127], v[126:127], v[158:159] op_sel_hi:[1,0]
	v_pk_mul_f32 v[128:129], v[128:129], v[158:159] op_sel_hi:[1,0]
	v_pk_mul_f32 v[122:123], v[122:123], v[158:159] op_sel_hi:[1,0]
	v_pk_mul_f32 v[124:125], v[124:125], v[158:159] op_sel_hi:[1,0]
	v_mul_f32_e32 v144, 0xbfb8aa3b, v126
	v_mul_f32_e32 v145, 0xbfb8aa3b, v127
	v_mul_f32_e32 v146, 0xbfb8aa3b, v128
	v_mul_f32_e32 v147, 0xbfb8aa3b, v129
	v_exp_f32_e32 v144, v144
	v_exp_f32_e32 v145, v145
	v_exp_f32_e32 v146, v146
	v_exp_f32_e32 v147, v147
	v_add_f32_e32 v144, 1.0, v144
	v_add_f32_e32 v145, 1.0, v145
	v_add_f32_e32 v146, 1.0, v146
	v_add_f32_e32 v147, 1.0, v147
	v_rcp_f32_e32 v144, v144
	v_rcp_f32_e32 v145, v145
	v_rcp_f32_e32 v146, v146
	v_rcp_f32_e32 v147, v147
	v_pk_mul_f32 v[126:127], v[126:127], v[144:145]
	v_pk_mul_f32 v[128:129], v[128:129], v[146:147]
	v_pk_mul_f32 v[126:127], v[126:127], v[122:123]
	v_pk_mul_f32 v[128:129], v[128:129], v[124:125]
	v_cvt_pk_bf16_f32 v122, v126, v127
	v_cvt_pk_bf16_f32 v123, v128, v129
	v_pk_mul_f32 v[118:119], v[118:119], v[158:159] op_sel_hi:[1,0]
	v_pk_mul_f32 v[120:121], v[120:121], v[158:159] op_sel_hi:[1,0]
	v_pk_mul_f32 v[114:115], v[114:115], v[158:159] op_sel_hi:[1,0]
	v_pk_mul_f32 v[116:117], v[116:117], v[158:159] op_sel_hi:[1,0]
	v_pk_mul_f32 v[110:111], v[110:111], v[158:159] op_sel:[0,1]
	v_pk_mul_f32 v[112:113], v[112:113], v[158:159] op_sel:[0,1]
	v_pk_mul_f32 v[106:107], v[106:107], v[158:159] op_sel:[0,1]
	v_pk_mul_f32 v[108:109], v[108:109], v[158:159] op_sel:[0,1]
	v_mul_f32_e32 v144, 0xbfb8aa3b, v118
; DI unsigned pk2(float lo, float hi) { f32x2 v = {lo, hi}; bf2_t r = __builtin_convertvector(v, bf2_t); return __builtin_bit_cast(unsigned, r); }
; DI float silu(float x) { return x * __builtin_amdgcn_rcpf(1.f + __expf(-x)); }
; #define PG8_LAS __attribute__((address_space(3)))
;   DI void operator()(const f32x4 (&acc)[2][2][4][2], const Unit& u, int wr, int wc, int fr, int fq, const PG8_LAS float* sR) const {
;     const int row0 = u.pm * BM + wr * 64 + fr, j0 = (u.pn * BM + wc * 32) / 2 + 4 * fq;
; #pragma unroll
;     for (int ai = 0; ai < 2; ++ai)
; #pragma unroll
;       for (int m = 0; m < 4; ++m) {
;         bf16_t* rowp = Hd + (size_t)(row0 + ai * HALF + m * 16) * 2816 + j0;
;         const float rs = sR[ai * 128 + m * 16 + fr];
; #pragma unroll
;         for (int bj = 0; bj < 2; ++bj) {
;           const f32x4 g = acc[ai][bj][m][0] * rs, up = acc[ai][bj][m][1] * rs;
;           u32x2 o; o[0] = pk2(silu(g[0]) * up[0], silu(g[1]) * up[1]); o[1] = pk2(silu(g[2]) * up[2], silu(g[3]) * up[3]);
;           *(u32x2*)(rowp + bj * (HALF / 2)) = o;
;         }
;       }
	v_mul_f32_e32 v145, 0xbfb8aa3b, v119
	v_mul_f32_e32 v146, 0xbfb8aa3b, v120
	v_mul_f32_e32 v147, 0xbfb8aa3b, v121
	v_mul_f32_e32 v126, 0xbfb8aa3b, v110
	v_mul_f32_e32 v127, 0xbfb8aa3b, v111
	v_mul_f32_e32 v128, 0xbfb8aa3b, v112
	v_mul_f32_e32 v129, 0xbfb8aa3b, v113
	v_exp_f32_e32 v144, v144
	v_exp_f32_e32 v145, v145
	v_exp_f32_e32 v146, v146
	v_exp_f32_e32 v147, v147
	v_exp_f32_e32 v126, v126
	v_exp_f32_e32 v127, v127
	v_exp_f32_e32 v128, v128
	v_exp_f32_e32 v129, v129
	v_add_f32_e32 v144, 1.0, v144
	v_add_f32_e32 v145, 1.0, v145
	v_add_f32_e32 v146, 1.0, v146
	v_add_f32_e32 v147, 1.0, v147
	v_add_f32_e32 v126, 1.0, v126
	v_add_f32_e32 v127, 1.0, v127
	v_add_f32_e32 v128, 1.0, v128
	v_add_f32_e32 v129, 1.0, v129
	v_rcp_f32_e32 v144, v144
	v_rcp_f32_e32 v145, v145
	v_rcp_f32_e32 v146, v146
	v_rcp_f32_e32 v147, v147
	v_rcp_f32_e32 v126, v126
	v_rcp_f32_e32 v127, v127
	v_rcp_f32_e32 v128, v128
	v_rcp_f32_e32 v129, v129
	v_pk_mul_f32 v[118:119], v[118:119], v[144:145]
	v_pk_mul_f32 v[120:121], v[120:121], v[146:147]
	v_pk_mul_f32 v[110:111], v[110:111], v[126:127]
	v_pk_mul_f32 v[112:113], v[112:113], v[128:129]
	v_pk_mul_f32 v[118:119], v[118:119], v[114:115]
	v_pk_mul_f32 v[120:121], v[120:121], v[116:117]
	v_pk_mul_f32 v[110:111], v[110:111], v[106:107]
	v_pk_mul_f32 v[112:113], v[112:113], v[108:109]
	v_cvt_pk_bf16_f32 v124, v118, v119
	v_cvt_pk_bf16_f32 v125, v120, v121
	v_cvt_pk_bf16_f32 v106, v110, v111
	v_cvt_pk_bf16_f32 v107, v112, v113
	s_nop 1
	v_permlane16_swap_b32_e32 v122, v124
	v_permlane16_swap_b32_e32 v123, v125
	global_store_dwordx4 v[156:157], v[122:125], off
	v_lshl_add_u64 v[156:157], v[156:157], 0, s[56:57]
	ds_read2_b32 v[118:119], v154 offset0:128 offset1:144
	ds_read2_b32 v[120:121], v154 offset0:160 offset1:176
	v_pk_mul_f32 v[102:103], v[102:103], v[158:159] op_sel:[0,1]
	v_pk_mul_f32 v[104:105], v[104:105], v[158:159] op_sel:[0,1]
	v_pk_mul_f32 v[98:99], v[98:99], v[158:159] op_sel:[0,1]
	v_pk_mul_f32 v[100:101], v[100:101], v[158:159] op_sel:[0,1]
	v_pk_mul_f32 v[94:95], v[94:95], v[160:161] op_sel_hi:[1,0]
	v_pk_mul_f32 v[96:97], v[96:97], v[160:161] op_sel_hi:[1,0]
	v_pk_mul_f32 v[90:91], v[90:91], v[160:161] op_sel_hi:[1,0]
	v_pk_mul_f32 v[92:93], v[92:93], v[160:161] op_sel_hi:[1,0]
	v_mul_f32_e32 v144, 0xbfb8aa3b, v102
	v_mul_f32_e32 v145, 0xbfb8aa3b, v103
	v_mul_f32_e32 v146, 0xbfb8aa3b, v104
	v_mul_f32_e32 v147, 0xbfb8aa3b, v105
	v_mul_f32_e32 v126, 0xbfb8aa3b, v94
	v_mul_f32_e32 v127, 0xbfb8aa3b, v95
	v_mul_f32_e32 v128, 0xbfb8aa3b, v96
	v_mul_f32_e32 v129, 0xbfb8aa3b, v97
	v_exp_f32_e32 v144, v144
	v_exp_f32_e32 v145, v145
	v_exp_f32_e32 v146, v146
	v_exp_f32_e32 v147, v147
	v_exp_f32_e32 v126, v126
	v_exp_f32_e32 v127, v127
	v_exp_f32_e32 v128, v128
	v_exp_f32_e32 v129, v129
	v_add_f32_e32 v144, 1.0, v144
	v_add_f32_e32 v145, 1.0, v145
	v_add_f32_e32 v146, 1.0, v146
	v_add_f32_e32 v147, 1.0, v147
	v_add_f32_e32 v126, 1.0, v126
	v_add_f32_e32 v127, 1.0, v127
	v_add_f32_e32 v128, 1.0, v128
	v_add_f32_e32 v129, 1.0, v129
	v_rcp_f32_e32 v144, v144
	v_rcp_f32_e32 v145, v145
	v_rcp_f32_e32 v146, v146
	v_rcp_f32_e32 v147, v147
	v_rcp_f32_e32 v126, v126
	v_rcp_f32_e32 v127, v127
	v_rcp_f32_e32 v128, v128
	v_rcp_f32_e32 v129, v129
	v_pk_mul_f32 v[102:103], v[102:103], v[144:145]
	v_pk_mul_f32 v[104:105], v[104:105], v[146:147]
	v_pk_mul_f32 v[94:95], v[94:95], v[126:127]
	v_pk_mul_f32 v[96:97], v[96:97], v[128:129]
	v_pk_mul_f32 v[102:103], v[102:103], v[98:99]
	v_pk_mul_f32 v[104:105], v[104:105], v[100:101]
	v_pk_mul_f32 v[94:95], v[94:95], v[90:91]
	v_pk_mul_f32 v[96:97], v[96:97], v[92:93]
	v_cvt_pk_bf16_f32 v108, v102, v103
	v_cvt_pk_bf16_f32 v109, v104, v105
	v_cvt_pk_bf16_f32 v90, v94, v95
	v_cvt_pk_bf16_f32 v91, v96, v97
	s_nop 1
	v_permlane16_swap_b32_e32 v106, v108
	v_permlane16_swap_b32_e32 v107, v109
	global_store_dwordx4 v[156:157], v[106:109], off
	v_lshl_add_u64 v[156:157], v[156:157], 0, s[56:57]
	v_pk_mul_f32 v[86:87], v[86:87], v[160:161] op_sel_hi:[1,0]
	v_pk_mul_f32 v[88:89], v[88:89], v[160:161] op_sel_hi:[1,0]
	v_pk_mul_f32 v[82:83], v[82:83], v[160:161] op_sel_hi:[1,0]
	v_pk_mul_f32 v[84:85], v[84:85], v[160:161] op_sel_hi:[1,0]
	v_pk_mul_f32 v[78:79], v[78:79], v[160:161] op_sel:[0,1]
	v_pk_mul_f32 v[80:81], v[80:81], v[160:161] op_sel:[0,1]
	v_pk_mul_f32 v[74:75], v[74:75], v[160:161] op_sel:[0,1]
	v_pk_mul_f32 v[76:77], v[76:77], v[160:161] op_sel:[0,1]
	v_mul_f32_e32 v144, 0xbfb8aa3b, v86
	v_mul_f32_e32 v145, 0xbfb8aa3b, v87
	v_mul_f32_e32 v146, 0xbfb8aa3b, v88
	v_mul_f32_e32 v147, 0xbfb8aa3b, v89
	v_mul_f32_e32 v126, 0xbfb8aa3b, v78
	v_mul_f32_e32 v127, 0xbfb8aa3b, v79
	v_mul_f32_e32 v128, 0xbfb8aa3b, v80
	v_mul_f32_e32 v129, 0xbfb8aa3b, v81
	v_exp_f32_e32 v144, v144
	v_exp_f32_e32 v145, v145
	v_exp_f32_e32 v146, v146
	v_exp_f32_e32 v147, v147
	v_exp_f32_e32 v126, v126
	v_exp_f32_e32 v127, v127
	v_exp_f32_e32 v128, v128
	v_exp_f32_e32 v129, v129
	v_add_f32_e32 v144, 1.0, v144
	v_add_f32_e32 v145, 1.0, v145
	v_add_f32_e32 v146, 1.0, v146
	v_add_f32_e32 v147, 1.0, v147
	v_add_f32_e32 v126, 1.0, v126
	v_add_f32_e32 v127, 1.0, v127
	v_add_f32_e32 v128, 1.0, v128
	v_add_f32_e32 v129, 1.0, v129
	v_rcp_f32_e32 v144, v144
	v_rcp_f32_e32 v145, v145
	v_rcp_f32_e32 v146, v146
	v_rcp_f32_e32 v147, v147
	v_rcp_f32_e32 v126, v126
	v_rcp_f32_e32 v127, v127
	v_rcp_f32_e32 v128, v128
	v_rcp_f32_e32 v129, v129
	v_pk_mul_f32 v[86:87], v[86:87], v[144:145]
	v_pk_mul_f32 v[88:89], v[88:89], v[146:147]
	v_pk_mul_f32 v[78:79], v[78:79], v[126:127]
	v_pk_mul_f32 v[80:81], v[80:81], v[128:129]
	v_pk_mul_f32 v[86:87], v[86:87], v[82:83]
	v_pk_mul_f32 v[88:89], v[88:89], v[84:85]
	v_pk_mul_f32 v[78:79], v[78:79], v[74:75]
	v_pk_mul_f32 v[80:81], v[80:81], v[76:77]
	v_cvt_pk_bf16_f32 v92, v86, v87
	v_cvt_pk_bf16_f32 v93, v88, v89
	v_cvt_pk_bf16_f32 v74, v78, v79
	v_cvt_pk_bf16_f32 v75, v80, v81
	s_nop 1
	v_permlane16_swap_b32_e32 v90, v92
	v_permlane16_swap_b32_e32 v91, v93
	global_store_dwordx4 v[156:157], v[90:93], off
	v_lshl_add_u64 v[156:157], v[156:157], 0, s[56:57]
	s_waitcnt lgkmcnt(0)
; DI unsigned pk2(float lo, float hi) { f32x2 v = {lo, hi}; bf2_t r = __builtin_convertvector(v, bf2_t); return __builtin_bit_cast(unsigned, r); }
; DI float silu(float x) { return x * __builtin_amdgcn_rcpf(1.f + __expf(-x)); }
; #define PG8_LAS __attribute__((address_space(3)))
;   DI void operator()(const f32x4 (&acc)[2][2][4][2], const Unit& u, int wr, int wc, int fr, int fq, const PG8_LAS float* sR) const {
;     const int row0 = u.pm * BM + wr * 64 + fr, j0 = (u.pn * BM + wc * 32) / 2 + 4 * fq;
; #pragma unroll
;     for (int ai = 0; ai < 2; ++ai)
; #pragma unroll
;       for (int m = 0; m < 4; ++m) {
;         bf16_t* rowp = Hd + (size_t)(row0 + ai * HALF + m * 16) * 2816 + j0;
;         const float rs = sR[ai * 128 + m * 16 + fr];
; #pragma unroll
;         for (int bj = 0; bj < 2; ++bj) {
;           const f32x4 g = acc[ai][bj][m][0] * rs, up = acc[ai][bj][m][1] * rs;
;           u32x2 o; o[0] = pk2(silu(g[0]) * up[0], silu(g[1]) * up[1]); o[1] = pk2(silu(g[2]) * up[2], silu(g[3]) * up[3]);
;           *(u32x2*)(rowp + bj * (HALF / 2)) = o;
;         }
;       }
	v_pk_mul_f32 v[70:71], v[70:71], v[160:161] op_sel:[0,1]
	v_pk_mul_f32 v[72:73], v[72:73], v[160:161] op_sel:[0,1]
	v_pk_mul_f32 v[66:67], v[66:67], v[160:161] op_sel:[0,1]
	v_pk_mul_f32 v[68:69], v[68:69], v[160:161] op_sel:[0,1]
	v_pk_mul_f32 v[62:63], v[62:63], v[118:119] op_sel_hi:[1,0]
	v_pk_mul_f32 v[64:65], v[64:65], v[118:119] op_sel_hi:[1,0]
	v_pk_mul_f32 v[58:59], v[58:59], v[118:119] op_sel_hi:[1,0]
	v_pk_mul_f32 v[60:61], v[60:61], v[118:119] op_sel_hi:[1,0]
	v_mul_f32_e32 v144, 0xbfb8aa3b, v70
	v_mul_f32_e32 v145, 0xbfb8aa3b, v71
	v_mul_f32_e32 v146, 0xbfb8aa3b, v72
	v_mul_f32_e32 v147, 0xbfb8aa3b, v73
	v_mul_f32_e32 v126, 0xbfb8aa3b, v62
	v_mul_f32_e32 v127, 0xbfb8aa3b, v63
	v_mul_f32_e32 v128, 0xbfb8aa3b, v64
	v_mul_f32_e32 v129, 0xbfb8aa3b, v65
	v_exp_f32_e32 v144, v144
	v_exp_f32_e32 v145, v145
	v_exp_f32_e32 v146, v146
	v_exp_f32_e32 v147, v147
	v_exp_f32_e32 v126, v126
	v_exp_f32_e32 v127, v127
	v_exp_f32_e32 v128, v128
	v_exp_f32_e32 v129, v129
	v_add_f32_e32 v144, 1.0, v144
	v_add_f32_e32 v145, 1.0, v145
	v_add_f32_e32 v146, 1.0, v146
	v_add_f32_e32 v147, 1.0, v147
	v_add_f32_e32 v126, 1.0, v126
	v_add_f32_e32 v127, 1.0, v127
	v_add_f32_e32 v128, 1.0, v128
	v_add_f32_e32 v129, 1.0, v129
	v_rcp_f32_e32 v144, v144
	v_rcp_f32_e32 v145, v145
	v_rcp_f32_e32 v146, v146
	v_rcp_f32_e32 v147, v147
	v_rcp_f32_e32 v126, v126
	v_rcp_f32_e32 v127, v127
	v_rcp_f32_e32 v128, v128
	v_rcp_f32_e32 v129, v129
	v_pk_mul_f32 v[70:71], v[70:71], v[144:145]
	v_pk_mul_f32 v[72:73], v[72:73], v[146:147]
	v_pk_mul_f32 v[62:63], v[62:63], v[126:127]
	v_pk_mul_f32 v[64:65], v[64:65], v[128:129]
	v_pk_mul_f32 v[70:71], v[70:71], v[66:67]
	v_pk_mul_f32 v[72:73], v[72:73], v[68:69]
	v_pk_mul_f32 v[62:63], v[62:63], v[58:59]
	v_pk_mul_f32 v[64:65], v[64:65], v[60:61]
	v_cvt_pk_bf16_f32 v76, v70, v71
	v_cvt_pk_bf16_f32 v77, v72, v73
	v_cvt_pk_bf16_f32 v58, v62, v63
	v_cvt_pk_bf16_f32 v59, v64, v65
	s_nop 1
	v_permlane16_swap_b32_e32 v74, v76
	v_permlane16_swap_b32_e32 v75, v77
	global_store_dwordx4 v[156:157], v[74:77], off
	s_mov_b32 s56, 0x6e000
	v_lshl_add_u64 v[156:157], v[156:157], 0, s[56:57]
	s_mov_b32 s56, 0x16000
	v_pk_mul_f32 v[54:55], v[54:55], v[118:119] op_sel_hi:[1,0]
	v_pk_mul_f32 v[56:57], v[56:57], v[118:119] op_sel_hi:[1,0]
	v_pk_mul_f32 v[50:51], v[50:51], v[118:119] op_sel_hi:[1,0]
	v_pk_mul_f32 v[52:53], v[52:53], v[118:119] op_sel_hi:[1,0]
	v_pk_mul_f32 v[46:47], v[46:47], v[118:119] op_sel:[0,1]
	v_pk_mul_f32 v[48:49], v[48:49], v[118:119] op_sel:[0,1]
	v_pk_mul_f32 v[42:43], v[42:43], v[118:119] op_sel:[0,1]
	v_pk_mul_f32 v[44:45], v[44:45], v[118:119] op_sel:[0,1]
	v_mul_f32_e32 v144, 0xbfb8aa3b, v54
	v_mul_f32_e32 v145, 0xbfb8aa3b, v55
	v_mul_f32_e32 v146, 0xbfb8aa3b, v56
	v_mul_f32_e32 v147, 0xbfb8aa3b, v57
	v_mul_f32_e32 v126, 0xbfb8aa3b, v46
	v_mul_f32_e32 v127, 0xbfb8aa3b, v47
	v_mul_f32_e32 v128, 0xbfb8aa3b, v48
	v_mul_f32_e32 v129, 0xbfb8aa3b, v49
	v_exp_f32_e32 v144, v144
	v_exp_f32_e32 v145, v145
	v_exp_f32_e32 v146, v146
	v_exp_f32_e32 v147, v147
	v_exp_f32_e32 v126, v126
	v_exp_f32_e32 v127, v127
	v_exp_f32_e32 v128, v128
	v_exp_f32_e32 v129, v129
	v_add_f32_e32 v144, 1.0, v144
	v_add_f32_e32 v145, 1.0, v145
	v_add_f32_e32 v146, 1.0, v146
	v_add_f32_e32 v147, 1.0, v147
	v_add_f32_e32 v126, 1.0, v126
	v_add_f32_e32 v127, 1.0, v127
	v_add_f32_e32 v128, 1.0, v128
	v_add_f32_e32 v129, 1.0, v129
	v_rcp_f32_e32 v144, v144
	v_rcp_f32_e32 v145, v145
	v_rcp_f32_e32 v146, v146
	v_rcp_f32_e32 v147, v147
	v_rcp_f32_e32 v126, v126
	v_rcp_f32_e32 v127, v127
	v_rcp_f32_e32 v128, v128
	v_rcp_f32_e32 v129, v129
	v_pk_mul_f32 v[54:55], v[54:55], v[144:145]
	v_pk_mul_f32 v[56:57], v[56:57], v[146:147]
	v_pk_mul_f32 v[46:47], v[46:47], v[126:127]
	v_pk_mul_f32 v[48:49], v[48:49], v[128:129]
	v_pk_mul_f32 v[54:55], v[54:55], v[50:51]
	v_pk_mul_f32 v[56:57], v[56:57], v[52:53]
	v_pk_mul_f32 v[46:47], v[46:47], v[42:43]
	v_pk_mul_f32 v[48:49], v[48:49], v[44:45]
	v_cvt_pk_bf16_f32 v60, v54, v55
	v_cvt_pk_bf16_f32 v61, v56, v57
	v_cvt_pk_bf16_f32 v42, v46, v47
	v_cvt_pk_bf16_f32 v43, v48, v49
	s_nop 1
	v_permlane16_swap_b32_e32 v58, v60
	v_permlane16_swap_b32_e32 v59, v61
	global_store_dwordx4 v[156:157], v[58:61], off
	v_lshl_add_u64 v[156:157], v[156:157], 0, s[56:57]
	v_pk_mul_f32 v[38:39], v[38:39], v[118:119] op_sel:[0,1]
	v_pk_mul_f32 v[40:41], v[40:41], v[118:119] op_sel:[0,1]
	v_pk_mul_f32 v[34:35], v[34:35], v[118:119] op_sel:[0,1]
	v_pk_mul_f32 v[36:37], v[36:37], v[118:119] op_sel:[0,1]
	v_pk_mul_f32 v[30:31], v[30:31], v[120:121] op_sel_hi:[1,0]
	v_pk_mul_f32 v[32:33], v[32:33], v[120:121] op_sel_hi:[1,0]
	v_pk_mul_f32 v[26:27], v[26:27], v[120:121] op_sel_hi:[1,0]
	v_pk_mul_f32 v[28:29], v[28:29], v[120:121] op_sel_hi:[1,0]
	v_mul_f32_e32 v144, 0xbfb8aa3b, v38
	v_mul_f32_e32 v145, 0xbfb8aa3b, v39
	v_mul_f32_e32 v146, 0xbfb8aa3b, v40
; DI unsigned pk2(float lo, float hi) { f32x2 v = {lo, hi}; bf2_t r = __builtin_convertvector(v, bf2_t); return __builtin_bit_cast(unsigned, r); }
; DI float silu(float x) { return x * __builtin_amdgcn_rcpf(1.f + __expf(-x)); }
;   DI void operator()(const f32x4 (&acc)[2][2][4][2], const Unit& u, int wr, int wc, int fr, int fq, const PG8_LAS float* sR) const {
;     ...
;     for (int ai = 0; ai < 2; ++ai)
; #pragma unroll
;       for (int m = 0; m < 4; ++m) {
;         bf16_t* rowp = Hd + (size_t)(row0 + ai * HALF + m * 16) * 2816 + j0;
;         const float rs = sR[ai * 128 + m * 16 + fr];
; #pragma unroll
;         for (int bj = 0; bj < 2; ++bj) {
;           const f32x4 g = acc[ai][bj][m][0] * rs, up = acc[ai][bj][m][1] * rs;
;           u32x2 o; o[0] = pk2(silu(g[0]) * up[0], silu(g[1]) * up[1]); o[1] = pk2(silu(g[2]) * up[2], silu(g[3]) * up[3]);
;           *(u32x2*)(rowp + bj * (HALF / 2)) = o;
;         }
;       }
; template <class Epi>
; DI void gemm_phase(PG8_LAS unsigned char* lds, const Gemm g, const StaticOrder& S, const Epi& E) {
;     ...
;     if (!has_next) break;
; #pragma unroll
;     for (int a = 0; a < 2; ++a)
; #pragma unroll
;       for (int b = 0; b < 2; ++b)
; #pragma unroll
;         for (int m = 0; m < 4; ++m)
; #pragma unroll
;           for (int n = 0; n < 2; ++n) acc[a][b][m][n] = (f32x4){0.f, 0.f, 0.f, 0.f};
;     cur = nxt; cA = nA; cB = nB; ++ui;
	v_mul_f32_e32 v147, 0xbfb8aa3b, v41
	v_mul_f32_e32 v126, 0xbfb8aa3b, v30
	v_mul_f32_e32 v127, 0xbfb8aa3b, v31
	v_mul_f32_e32 v128, 0xbfb8aa3b, v32
	v_mul_f32_e32 v129, 0xbfb8aa3b, v33
	v_exp_f32_e32 v144, v144
	v_exp_f32_e32 v145, v145
	v_exp_f32_e32 v146, v146
	v_exp_f32_e32 v147, v147
	v_exp_f32_e32 v126, v126
	v_exp_f32_e32 v127, v127
	v_exp_f32_e32 v128, v128
	v_exp_f32_e32 v129, v129
	v_add_f32_e32 v144, 1.0, v144
	v_add_f32_e32 v145, 1.0, v145
	v_add_f32_e32 v146, 1.0, v146
	v_add_f32_e32 v147, 1.0, v147
	v_add_f32_e32 v126, 1.0, v126
	v_add_f32_e32 v127, 1.0, v127
	v_add_f32_e32 v128, 1.0, v128
	v_add_f32_e32 v129, 1.0, v129
	v_rcp_f32_e32 v144, v144
	v_rcp_f32_e32 v145, v145
	v_rcp_f32_e32 v146, v146
	v_rcp_f32_e32 v147, v147
	v_rcp_f32_e32 v126, v126
	v_rcp_f32_e32 v127, v127
	v_rcp_f32_e32 v128, v128
	v_rcp_f32_e32 v129, v129
	v_pk_mul_f32 v[38:39], v[38:39], v[144:145]
	v_pk_mul_f32 v[40:41], v[40:41], v[146:147]
	v_pk_mul_f32 v[30:31], v[30:31], v[126:127]
	v_pk_mul_f32 v[32:33], v[32:33], v[128:129]
	v_pk_mul_f32 v[38:39], v[38:39], v[34:35]
	v_pk_mul_f32 v[40:41], v[40:41], v[36:37]
	v_pk_mul_f32 v[30:31], v[30:31], v[26:27]
	v_pk_mul_f32 v[32:33], v[32:33], v[28:29]
	v_cvt_pk_bf16_f32 v44, v38, v39
	v_cvt_pk_bf16_f32 v45, v40, v41
	v_cvt_pk_bf16_f32 v26, v30, v31
	v_cvt_pk_bf16_f32 v27, v32, v33
	s_nop 1
	v_permlane16_swap_b32_e32 v42, v44
	v_permlane16_swap_b32_e32 v43, v45
	global_store_dwordx4 v[156:157], v[42:45], off
	v_lshl_add_u64 v[156:157], v[156:157], 0, s[56:57]
	v_pk_mul_f32 v[22:23], v[22:23], v[120:121] op_sel_hi:[1,0]
	v_pk_mul_f32 v[24:25], v[24:25], v[120:121] op_sel_hi:[1,0]
	v_pk_mul_f32 v[18:19], v[18:19], v[120:121] op_sel_hi:[1,0]
	v_pk_mul_f32 v[20:21], v[20:21], v[120:121] op_sel_hi:[1,0]
	v_pk_mul_f32 v[14:15], v[14:15], v[120:121] op_sel:[0,1]
	v_pk_mul_f32 v[16:17], v[16:17], v[120:121] op_sel:[0,1]
	v_pk_mul_f32 v[10:11], v[10:11], v[120:121] op_sel:[0,1]
	v_pk_mul_f32 v[12:13], v[12:13], v[120:121] op_sel:[0,1]
	v_mul_f32_e32 v144, 0xbfb8aa3b, v22
	v_mul_f32_e32 v145, 0xbfb8aa3b, v23
	v_mul_f32_e32 v146, 0xbfb8aa3b, v24
	v_mul_f32_e32 v147, 0xbfb8aa3b, v25
	v_mul_f32_e32 v126, 0xbfb8aa3b, v14
	v_mul_f32_e32 v127, 0xbfb8aa3b, v15
	v_mul_f32_e32 v128, 0xbfb8aa3b, v16
	v_mul_f32_e32 v129, 0xbfb8aa3b, v17
	v_exp_f32_e32 v144, v144
	v_exp_f32_e32 v145, v145
	v_exp_f32_e32 v146, v146
	v_exp_f32_e32 v147, v147
	v_exp_f32_e32 v126, v126
	v_exp_f32_e32 v127, v127
	v_exp_f32_e32 v128, v128
	v_exp_f32_e32 v129, v129
	v_add_f32_e32 v144, 1.0, v144
	v_add_f32_e32 v145, 1.0, v145
	v_add_f32_e32 v146, 1.0, v146
	v_add_f32_e32 v147, 1.0, v147
	v_add_f32_e32 v126, 1.0, v126
	v_add_f32_e32 v127, 1.0, v127
	v_add_f32_e32 v128, 1.0, v128
	v_add_f32_e32 v129, 1.0, v129
	v_rcp_f32_e32 v144, v144
	v_rcp_f32_e32 v145, v145
	v_rcp_f32_e32 v146, v146
	v_rcp_f32_e32 v147, v147
	v_rcp_f32_e32 v126, v126
	v_rcp_f32_e32 v127, v127
	v_rcp_f32_e32 v128, v128
	v_rcp_f32_e32 v129, v129
	v_pk_mul_f32 v[22:23], v[22:23], v[144:145]
	v_pk_mul_f32 v[24:25], v[24:25], v[146:147]
	v_pk_mul_f32 v[14:15], v[14:15], v[126:127]
	v_pk_mul_f32 v[16:17], v[16:17], v[128:129]
	v_pk_mul_f32 v[22:23], v[22:23], v[18:19]
	v_pk_mul_f32 v[24:25], v[24:25], v[20:21]
	v_pk_mul_f32 v[14:15], v[14:15], v[10:11]
	v_pk_mul_f32 v[16:17], v[16:17], v[12:13]
	v_cvt_pk_bf16_f32 v28, v22, v23
	v_cvt_pk_bf16_f32 v29, v24, v25
	v_cvt_pk_bf16_f32 v10, v14, v15
	v_cvt_pk_bf16_f32 v11, v16, v17
	s_nop 1
	v_permlane16_swap_b32_e32 v26, v28
	v_permlane16_swap_b32_e32 v27, v29
	global_store_dwordx4 v[156:157], v[26:29], off
	v_lshl_add_u64 v[156:157], v[156:157], 0, s[56:57]
	v_pk_mul_f32 v[6:7], v[6:7], v[120:121] op_sel:[0,1]
	v_pk_mul_f32 v[8:9], v[8:9], v[120:121] op_sel:[0,1]
	v_pk_mul_f32 v[2:3], v[2:3], v[120:121] op_sel:[0,1]
	v_pk_mul_f32 v[4:5], v[4:5], v[120:121] op_sel:[0,1]
	v_mul_f32_e32 v144, 0xbfb8aa3b, v6
	v_mul_f32_e32 v145, 0xbfb8aa3b, v7
	v_mul_f32_e32 v146, 0xbfb8aa3b, v8
	v_mul_f32_e32 v147, 0xbfb8aa3b, v9
	v_exp_f32_e32 v144, v144
	v_exp_f32_e32 v145, v145
	v_exp_f32_e32 v146, v146
	v_exp_f32_e32 v147, v147
	v_add_f32_e32 v144, 1.0, v144
	v_add_f32_e32 v145, 1.0, v145
	v_add_f32_e32 v146, 1.0, v146
	v_add_f32_e32 v147, 1.0, v147
	v_rcp_f32_e32 v144, v144
	v_rcp_f32_e32 v145, v145
	v_rcp_f32_e32 v146, v146
	v_rcp_f32_e32 v147, v147
	v_pk_mul_f32 v[6:7], v[6:7], v[144:145]
	v_pk_mul_f32 v[8:9], v[8:9], v[146:147]
	v_pk_mul_f32 v[6:7], v[6:7], v[2:3]
	v_pk_mul_f32 v[8:9], v[8:9], v[4:5]
	v_cvt_pk_bf16_f32 v12, v6, v7
	v_cvt_pk_bf16_f32 v13, v8, v9
	s_nop 1
	v_permlane16_swap_b32_e32 v10, v12
	v_permlane16_swap_b32_e32 v11, v13
	global_store_dwordx4 v[156:157], v[10:13], off
	s_mov_b32 s69, s68
	s_mov_b64 s[56:57], s[52:53]
	s_and_b64 vcc, exec, s[40:41]
	s_cbranch_vccz .LBB0_49
	s_waitcnt vmcnt(0)
	s_cmpk_gt_u32 s28, 0xff
	s_cbranch_scc1 .LBB0_56
	s_barrier

; DI unsigned pk2(float lo, float hi) { f32x2 v = {lo, hi}; bf2_t r = __builtin_convertvector(v, bf2_t); return __builtin_bit_cast(unsigned, r); }
; DI float bflo(unsigned u) { return __uint_as_float(u << 16); }
; DI float bfhi(unsigned u) { return __uint_as_float(u & 0xffff0000u); }
;   DI void operator()(const f32x4 (&acc)[2][2][4][2], const Unit& u, int wr, int wc, int fr, int fq, const PG8_LAS float* sR) const {
;     ...
; #pragma unroll
;       for (int m = 0; m < 4; ++m) {
;         const int row = row0 + ai * HALF + m * 16;
;         const size_t ro = (size_t)row * 1024 + col0;
;         float ss = 0.f;
; #pragma unroll
;         for (int bj = 0; bj < 2; ++bj)
; #pragma unroll
;           for (int n = 0; n < 2; ++n) {
;             f32x4 v;
;             if (X0 != nullptr) v = *(const f32x4*)(X0 + ro + bj * HALF + n * 16);
;             else { const u32x2 q = sv[m][bj][n]; v[0] = bflo(q[0]); v[1] = bfhi(q[0]); v[2] = bflo(q[1]); v[3] = bfhi(q[1]); }
;             v += acc[ai][bj][m][n];
;             ss += v[0] * v[0] + v[1] * v[1] + v[2] * v[2] + v[3] * v[3];
;             if (!dry) { u32x2 q; q[0] = pk2(v[0], v[1]); q[1] = pk2(v[2], v[3]); *(u32x2*)(S + ro + bj * HALF + n * 16) = q; }
;           }
;         ss += __shfl_xor(ss, 16); ss += __shfl_xor(ss, 32);
;         if (!dry && fq == 0) ssq[(size_t)row * 16 + u.pn * 4 + wc] = ss;
.LBB0_840:
	v_lshlrev_b64 v[130:131], 10, v[152:153]
	v_readlane_b32 s4, v253, 56
	v_lshl_add_u64 v[198:199], v[130:131], 0, v[154:155]
	v_readlane_b32 s5, v253, 57
	s_mov_b64 s[56:57], -1
	s_and_b64 vcc, exec, s[44:45]
	v_lshl_add_u64 v[196:197], v[198:199], 2, s[4:5]
	v_readlane_b32 s6, v253, 58
	v_readlane_b32 s7, v253, 59
	v_readlane_b32 s8, v253, 60
	v_readlane_b32 s9, v253, 61
	v_readlane_b32 s10, v253, 62
	v_readlane_b32 s11, v253, 63
	v_readlane_b32 s12, v254, 0
	v_readlane_b32 s13, v254, 1
	v_readlane_b32 s14, v254, 2
	v_readlane_b32 s15, v254, 3
	v_readlane_b32 s16, v254, 4
	v_readlane_b32 s17, v254, 5
	v_readlane_b32 s18, v254, 6
	v_readlane_b32 s19, v254, 7
	s_cbranch_vccnz .LBB0_842
	global_load_dwordx4 v[130:133], v[196:197], off
	s_waitcnt vmcnt(0)
	s_mov_b64 s[56:57], 0
.LBB0_842:
	s_andn2_b64 vcc, exec, s[56:57]
	s_cbranch_vccnz .LBB0_844
	s_waitcnt vmcnt(15)
	v_lshlrev_b32_e32 v130, 16, v194
	v_and_b32_e32 v131, 0xffff0000, v194
	v_lshlrev_b32_e32 v132, 16, v195
	v_and_b32_e32 v133, 0xffff0000, v195
.LBB0_844:
	v_pk_add_f32 v[132:133], v[128:129], v[132:133]
	v_pk_add_f32 v[194:195], v[126:127], v[130:131]
	v_cvt_pk_bf16_f32 v127, v132, v133
	v_cvt_pk_bf16_f32 v126, v194, v195
	v_lshl_add_u64 v[130:131], v[198:199], 1, s[22:23]
	s_and_b64 vcc, exec, s[44:45]
	s_mov_b64 s[56:57], -1
	global_store_dwordx2 v[130:131], v[126:127], off
	s_cbranch_vccnz .LBB0_846
	global_load_dwordx4 v[126:129], v[196:197], off offset:64
	s_waitcnt vmcnt(0)
	s_mov_b64 s[56:57], 0
.LBB0_846:
	s_andn2_b64 vcc, exec, s[56:57]
	s_cbranch_vccnz .LBB0_848
	s_waitcnt vmcnt(15)
	v_lshlrev_b32_e32 v126, 16, v192
	v_and_b32_e32 v127, 0xffff0000, v192
	v_lshlrev_b32_e32 v128, 16, v193
	v_and_b32_e32 v129, 0xffff0000, v193
.LBB0_848:
	v_pk_add_f32 v[128:129], v[124:125], v[128:129]
	v_pk_add_f32 v[126:127], v[122:123], v[126:127]
	v_cvt_pk_bf16_f32 v123, v128, v129
	v_cvt_pk_bf16_f32 v122, v126, v127
	s_and_b64 vcc, exec, s[44:45]
	s_mov_b64 s[56:57], -1
	global_store_dwordx2 v[130:131], v[122:123], off offset:32
	s_cbranch_vccnz .LBB0_850
	global_load_dwordx4 v[122:125], v[196:197], off offset:512
	s_waitcnt vmcnt(0)
	s_mov_b64 s[56:57], 0
.LBB0_850:
	s_andn2_b64 vcc, exec, s[56:57]
	s_cbranch_vccnz .LBB0_852
	s_waitcnt vmcnt(15)
	v_lshlrev_b32_e32 v122, 16, v190
	v_and_b32_e32 v123, 0xffff0000, v190
	v_lshlrev_b32_e32 v124, 16, v191
	v_and_b32_e32 v125, 0xffff0000, v191
.LBB0_852:
	v_pk_add_f32 v[124:125], v[120:121], v[124:125]
	v_pk_add_f32 v[122:123], v[118:119], v[122:123]
	v_cvt_pk_bf16_f32 v119, v124, v125
	v_cvt_pk_bf16_f32 v118, v122, v123
	s_and_b64 vcc, exec, s[44:45]
	s_mov_b64 s[56:57], -1
	global_store_dwordx2 v[130:131], v[118:119], off offset:256
	s_cbranch_vccnz .LBB0_854
	global_load_dwordx4 v[118:121], v[196:197], off offset:576
	s_waitcnt vmcnt(0)
	s_mov_b64 s[56:57], 0
.LBB0_854:
	s_andn2_b64 vcc, exec, s[56:57]
	s_cbranch_vccnz .LBB0_856
	s_waitcnt vmcnt(15)
	v_lshlrev_b32_e32 v118, 16, v188
	v_and_b32_e32 v119, 0xffff0000, v188
	v_lshlrev_b32_e32 v120, 16, v189
	v_and_b32_e32 v121, 0xffff0000, v189
.LBB0_856:
	v_mul_f32_e32 v188, v195, v195
	v_mul_f32_e32 v127, v127, v127
	v_fmac_f32_e32 v188, v194, v194
	v_fmac_f32_e32 v127, v126, v126
	v_mul_f32_e32 v123, v123, v123
	v_fmac_f32_e32 v188, v132, v132
	v_fmac_f32_e32 v127, v128, v128
	v_fmac_f32_e32 v123, v122, v122
	v_fmac_f32_e32 v188, v133, v133
	v_fmac_f32_e32 v127, v129, v129
	v_fmac_f32_e32 v123, v124, v124
	v_pk_add_f32 v[118:119], v[114:115], v[118:119]
	v_add_f32_e32 v126, v188, v127
	v_fmac_f32_e32 v123, v125, v125
	v_and_b32_e32 v124, 64, v204
	v_mul_f32_e32 v114, v119, v119
	v_add_f32_e32 v122, v126, v123
	v_xor_b32_e32 v123, 16, v204
	v_add_u32_e32 v125, 64, v124
	v_pk_add_f32 v[116:117], v[116:117], v[120:121]
	v_fmac_f32_e32 v114, v118, v118
	v_cmp_lt_i32_e32 vcc, v123, v125
	v_fmac_f32_e32 v114, v116, v116
	v_fmac_f32_e32 v114, v117, v117
	v_cndmask_b32_e32 v123, v204, v123, vcc
	v_lshlrev_b32_e32 v124, 2, v123
	v_add_f32_e32 v114, v122, v114
	ds_bpermute_b32 v115, v124, v114
	v_xor_b32_e32 v123, 32, v204
	v_cmp_lt_i32_e32 vcc, v123, v125
	s_lshl_b32 s56, s34, 2
	s_ashr_i32 s57, s56, 31
	v_cndmask_b32_e32 v120, v204, v123, vcc
	v_lshlrev_b32_e32 v125, 2, v120
	s_waitcnt lgkmcnt(0)
	v_add_f32_e32 v114, v114, v115
	ds_bpermute_b32 v115, v125, v114
	v_cvt_pk_bf16_f32 v118, v118, v119
	v_cvt_pk_bf16_f32 v119, v116, v117
	global_store_dwordx2 v[130:131], v[118:119], off offset:288
	s_and_saveexec_b64 s[58:59], s[40:41]
	s_cbranch_execz .LBB0_858
	s_waitcnt lgkmcnt(0)
	v_add_f32_e32 v116, v114, v115
	v_lshlrev_b64 v[114:115], 6, v[152:153]
	v_lshl_add_u64 v[114:115], s[92:93], 0, v[114:115]
	v_lshl_add_u64 v[114:115], s[56:57], 2, v[114:115]
	s_lshl_b32 s34, s70, 2
	v_lshl_add_u64 v[114:115], v[114:115], 0, s[34:35]
	global_store_dword v[114:115], v116, off
.LBB0_858:
	s_or_b64 exec, exec, s[58:59]
	s_waitcnt lgkmcnt(0)
	v_lshlrev_b64 v[114:115], 10, v[178:179]
	v_readlane_b32 s4, v253, 56
	v_lshl_add_u64 v[122:123], v[114:115], 0, v[154:155]
	v_readlane_b32 s5, v253, 57
	s_mov_b64 s[58:59], -1
	s_and_b64 vcc, exec, s[44:45]
	v_lshl_add_u64 v[118:119], v[122:123], 2, s[4:5]
	v_readlane_b32 s6, v253, 58
	v_readlane_b32 s7, v253, 59
	v_readlane_b32 s8, v253, 60
	v_readlane_b32 s9, v253, 61
	v_readlane_b32 s10, v253, 62
	v_readlane_b32 s11, v253, 63
	v_readlane_b32 s12, v254, 0
	v_readlane_b32 s13, v254, 1
	v_readlane_b32 s14, v254, 2
	v_readlane_b32 s15, v254, 3
	v_readlane_b32 s16, v254, 4
	v_readlane_b32 s17, v254, 5
	v_readlane_b32 s18, v254, 6
	v_readlane_b32 s19, v254, 7
	s_cbranch_vccnz .LBB0_860
	global_load_dwordx4 v[114:117], v[118:119], off
	s_waitcnt vmcnt(0)
	s_mov_b64 s[58:59], 0
; DI unsigned pk2(float lo, float hi) { f32x2 v = {lo, hi}; bf2_t r = __builtin_convertvector(v, bf2_t); return __builtin_bit_cast(unsigned, r); }
; DI float bflo(unsigned u) { return __uint_as_float(u << 16); }
; DI float bfhi(unsigned u) { return __uint_as_float(u & 0xffff0000u); }
;   DI void operator()(const f32x4 (&acc)[2][2][4][2], const Unit& u, int wr, int wc, int fr, int fq, const PG8_LAS float* sR) const {
;     ...
; #pragma unroll
;       for (int m = 0; m < 4; ++m) {
;         const int row = row0 + ai * HALF + m * 16;
;         const size_t ro = (size_t)row * 1024 + col0;
;         float ss = 0.f;
; #pragma unroll
;         for (int bj = 0; bj < 2; ++bj)
; #pragma unroll
;           for (int n = 0; n < 2; ++n) {
;             f32x4 v;
;             if (X0 != nullptr) v = *(const f32x4*)(X0 + ro + bj * HALF + n * 16);
;             else { const u32x2 q = sv[m][bj][n]; v[0] = bflo(q[0]); v[1] = bfhi(q[0]); v[2] = bflo(q[1]); v[3] = bfhi(q[1]); }
;             v += acc[ai][bj][m][n];
;             ss += v[0] * v[0] + v[1] * v[1] + v[2] * v[2] + v[3] * v[3];
;             if (!dry) { u32x2 q; q[0] = pk2(v[0], v[1]); q[1] = pk2(v[2], v[3]); *(u32x2*)(S + ro + bj * HALF + n * 16) = q; }
;           }
;         ss += __shfl_xor(ss, 16); ss += __shfl_xor(ss, 32);
;         if (!dry && fq == 0) ssq[(size_t)row * 16 + u.pn * 4 + wc] = ss;
.LBB0_860:
	s_andn2_b64 vcc, exec, s[58:59]
	s_cbranch_vccnz .LBB0_862
	s_waitcnt vmcnt(15)
	v_lshlrev_b32_e32 v114, 16, v186
	v_and_b32_e32 v115, 0xffff0000, v186
	v_lshlrev_b32_e32 v116, 16, v187
	v_and_b32_e32 v117, 0xffff0000, v187
.LBB0_862:
	v_pk_add_f32 v[116:117], v[112:113], v[116:117]
	v_pk_add_f32 v[120:121], v[110:111], v[114:115]
	v_cvt_pk_bf16_f32 v111, v116, v117
	v_cvt_pk_bf16_f32 v110, v120, v121
	v_lshl_add_u64 v[114:115], v[122:123], 1, s[22:23]
	s_and_b64 vcc, exec, s[44:45]
	s_mov_b64 s[58:59], -1
	global_store_dwordx2 v[114:115], v[110:111], off
	s_cbranch_vccnz .LBB0_864
	global_load_dwordx4 v[110:113], v[118:119], off offset:64
	s_waitcnt vmcnt(0)
	s_mov_b64 s[58:59], 0
.LBB0_864:
	s_andn2_b64 vcc, exec, s[58:59]
	s_cbranch_vccnz .LBB0_866
	s_waitcnt vmcnt(15)
	v_lshlrev_b32_e32 v110, 16, v184
	v_and_b32_e32 v111, 0xffff0000, v184
	v_lshlrev_b32_e32 v112, 16, v185
	v_and_b32_e32 v113, 0xffff0000, v185
.LBB0_866:
	v_pk_add_f32 v[112:113], v[108:109], v[112:113]
	v_pk_add_f32 v[110:111], v[106:107], v[110:111]
	v_cvt_pk_bf16_f32 v107, v112, v113
	v_cvt_pk_bf16_f32 v106, v110, v111
	s_and_b64 vcc, exec, s[44:45]
	s_mov_b64 s[58:59], -1
	global_store_dwordx2 v[114:115], v[106:107], off offset:32
	s_cbranch_vccnz .LBB0_868
	global_load_dwordx4 v[106:109], v[118:119], off offset:512
	s_waitcnt vmcnt(0)
	s_mov_b64 s[58:59], 0
.LBB0_868:
	s_andn2_b64 vcc, exec, s[58:59]
	s_cbranch_vccnz .LBB0_870
	s_waitcnt vmcnt(15)
	v_lshlrev_b32_e32 v106, 16, v182
	v_and_b32_e32 v107, 0xffff0000, v182
	v_lshlrev_b32_e32 v108, 16, v183
	v_and_b32_e32 v109, 0xffff0000, v183
.LBB0_870:
	v_pk_add_f32 v[108:109], v[104:105], v[108:109]
	v_pk_add_f32 v[106:107], v[102:103], v[106:107]
	v_cvt_pk_bf16_f32 v103, v108, v109
	v_cvt_pk_bf16_f32 v102, v106, v107
	s_and_b64 vcc, exec, s[44:45]
	s_mov_b64 s[58:59], -1
	global_store_dwordx2 v[114:115], v[102:103], off offset:256
	s_cbranch_vccnz .LBB0_872
	global_load_dwordx4 v[102:105], v[118:119], off offset:576
	s_waitcnt vmcnt(0)
	s_mov_b64 s[58:59], 0
.LBB0_872:
	s_andn2_b64 vcc, exec, s[58:59]
	s_cbranch_vccnz .LBB0_874
	s_waitcnt vmcnt(15)
	v_lshlrev_b32_e32 v102, 16, v180
	v_and_b32_e32 v103, 0xffff0000, v180
	v_lshlrev_b32_e32 v104, 16, v181
	v_and_b32_e32 v105, 0xffff0000, v181
.LBB0_874:
	v_mul_f32_e32 v118, v121, v121
	v_mul_f32_e32 v111, v111, v111
	v_fmac_f32_e32 v118, v120, v120
	v_fmac_f32_e32 v111, v110, v110
	v_mul_f32_e32 v107, v107, v107
	v_pk_add_f32 v[102:103], v[98:99], v[102:103]
	v_fmac_f32_e32 v118, v116, v116
	v_fmac_f32_e32 v111, v112, v112
	v_fmac_f32_e32 v107, v106, v106
	v_mul_f32_e32 v98, v103, v103
	v_fmac_f32_e32 v118, v117, v117
	v_fmac_f32_e32 v111, v113, v113
	v_fmac_f32_e32 v107, v108, v108
	v_pk_add_f32 v[100:101], v[100:101], v[104:105]
	v_fmac_f32_e32 v98, v102, v102
	v_add_f32_e32 v110, v118, v111
	v_fmac_f32_e32 v107, v109, v109
	v_fmac_f32_e32 v98, v100, v100
	v_add_f32_e32 v106, v110, v107
	v_fmac_f32_e32 v98, v101, v101
	v_add_f32_e32 v98, v106, v98
	ds_bpermute_b32 v99, v124, v98
	v_cvt_pk_bf16_f32 v102, v102, v103
	v_cvt_pk_bf16_f32 v103, v100, v101
	global_store_dwordx2 v[114:115], v[102:103], off offset:288
	s_waitcnt lgkmcnt(0)
	v_add_f32_e32 v98, v98, v99
	ds_bpermute_b32 v99, v125, v98
	s_and_saveexec_b64 s[58:59], s[40:41]
	s_cbranch_execz .LBB0_876
	s_waitcnt lgkmcnt(0)
	v_add_f32_e32 v100, v98, v99
	v_lshlrev_b64 v[98:99], 6, v[178:179]
	v_lshl_add_u64 v[98:99], s[92:93], 0, v[98:99]
	v_lshl_add_u64 v[98:99], s[56:57], 2, v[98:99]
	s_lshl_b32 s34, s70, 2
	v_lshl_add_u64 v[98:99], v[98:99], 0, s[34:35]
	global_store_dword v[98:99], v100, off
.LBB0_876:
	s_or_b64 exec, exec, s[58:59]
	s_waitcnt lgkmcnt(0)
	v_lshlrev_b64 v[98:99], 10, v[168:169]
	v_readlane_b32 s4, v253, 56
	v_lshl_add_u64 v[106:107], v[98:99], 0, v[154:155]
	v_readlane_b32 s5, v253, 57
	s_mov_b64 s[58:59], -1
	s_and_b64 vcc, exec, s[44:45]
	v_lshl_add_u64 v[102:103], v[106:107], 2, s[4:5]
	v_readlane_b32 s6, v253, 58
	v_readlane_b32 s7, v253, 59
	v_readlane_b32 s8, v253, 60
	v_readlane_b32 s9, v253, 61
	v_readlane_b32 s10, v253, 62
	v_readlane_b32 s11, v253, 63
	v_readlane_b32 s12, v254, 0
	v_readlane_b32 s13, v254, 1
	v_readlane_b32 s14, v254, 2
	v_readlane_b32 s15, v254, 3
	v_readlane_b32 s16, v254, 4
	v_readlane_b32 s17, v254, 5
	v_readlane_b32 s18, v254, 6
	v_readlane_b32 s19, v254, 7
	s_cbranch_vccnz .LBB0_878
	global_load_dwordx4 v[98:101], v[102:103], off
	s_waitcnt vmcnt(0)
	s_mov_b64 s[58:59], 0
.LBB0_878:
	s_andn2_b64 vcc, exec, s[58:59]
	s_cbranch_vccnz .LBB0_880
	s_waitcnt vmcnt(15)
	v_lshlrev_b32_e32 v98, 16, v176
	v_and_b32_e32 v99, 0xffff0000, v176
	v_lshlrev_b32_e32 v100, 16, v177
	v_and_b32_e32 v101, 0xffff0000, v177
.LBB0_880:
	v_pk_add_f32 v[100:101], v[96:97], v[100:101]
	v_pk_add_f32 v[104:105], v[94:95], v[98:99]
	v_cvt_pk_bf16_f32 v95, v100, v101
	v_cvt_pk_bf16_f32 v94, v104, v105
	v_lshl_add_u64 v[98:99], v[106:107], 1, s[22:23]
	s_and_b64 vcc, exec, s[44:45]
	s_mov_b64 s[58:59], -1
	global_store_dwordx2 v[98:99], v[94:95], off
	s_cbranch_vccnz .LBB0_882
	global_load_dwordx4 v[94:97], v[102:103], off offset:64
	s_waitcnt vmcnt(0)
	s_mov_b64 s[58:59], 0
.LBB0_882:
	s_andn2_b64 vcc, exec, s[58:59]
	s_cbranch_vccnz .LBB0_884
	s_waitcnt vmcnt(15)
	v_lshlrev_b32_e32 v94, 16, v174
	v_and_b32_e32 v95, 0xffff0000, v174
	v_lshlrev_b32_e32 v96, 16, v175
	v_and_b32_e32 v97, 0xffff0000, v175
.LBB0_884:
	v_pk_add_f32 v[96:97], v[92:93], v[96:97]
	v_pk_add_f32 v[94:95], v[90:91], v[94:95]
	v_cvt_pk_bf16_f32 v91, v96, v97
	v_cvt_pk_bf16_f32 v90, v94, v95
	s_and_b64 vcc, exec, s[44:45]
	s_mov_b64 s[58:59], -1
	global_store_dwordx2 v[98:99], v[90:91], off offset:32
	s_cbranch_vccnz .LBB0_886
	global_load_dwordx4 v[90:93], v[102:103], off offset:512
	s_waitcnt vmcnt(0)
	s_mov_b64 s[58:59], 0
; DI unsigned pk2(float lo, float hi) { f32x2 v = {lo, hi}; bf2_t r = __builtin_convertvector(v, bf2_t); return __builtin_bit_cast(unsigned, r); }
; DI float bflo(unsigned u) { return __uint_as_float(u << 16); }
; DI float bfhi(unsigned u) { return __uint_as_float(u & 0xffff0000u); }
;   DI void operator()(const f32x4 (&acc)[2][2][4][2], const Unit& u, int wr, int wc, int fr, int fq, const PG8_LAS float* sR) const {
;     ...
; #pragma unroll
;       for (int m = 0; m < 4; ++m) {
;         const int row = row0 + ai * HALF + m * 16;
;         const size_t ro = (size_t)row * 1024 + col0;
;         float ss = 0.f;
; #pragma unroll
;         for (int bj = 0; bj < 2; ++bj)
; #pragma unroll
;           for (int n = 0; n < 2; ++n) {
;             f32x4 v;
;             if (X0 != nullptr) v = *(const f32x4*)(X0 + ro + bj * HALF + n * 16);
;             else { const u32x2 q = sv[m][bj][n]; v[0] = bflo(q[0]); v[1] = bfhi(q[0]); v[2] = bflo(q[1]); v[3] = bfhi(q[1]); }
;             v += acc[ai][bj][m][n];
;             ss += v[0] * v[0] + v[1] * v[1] + v[2] * v[2] + v[3] * v[3];
;             if (!dry) { u32x2 q; q[0] = pk2(v[0], v[1]); q[1] = pk2(v[2], v[3]); *(u32x2*)(S + ro + bj * HALF + n * 16) = q; }
;           }
;         ss += __shfl_xor(ss, 16); ss += __shfl_xor(ss, 32);
;         if (!dry && fq == 0) ssq[(size_t)row * 16 + u.pn * 4 + wc] = ss;
.LBB0_886:
	s_andn2_b64 vcc, exec, s[58:59]
	s_cbranch_vccnz .LBB0_888
	s_waitcnt vmcnt(15)
	v_lshlrev_b32_e32 v90, 16, v172
	v_and_b32_e32 v91, 0xffff0000, v172
	v_lshlrev_b32_e32 v92, 16, v173
	v_and_b32_e32 v93, 0xffff0000, v173
.LBB0_888:
	v_pk_add_f32 v[92:93], v[88:89], v[92:93]
	v_pk_add_f32 v[90:91], v[86:87], v[90:91]
	v_cvt_pk_bf16_f32 v87, v92, v93
	v_cvt_pk_bf16_f32 v86, v90, v91
	s_and_b64 vcc, exec, s[44:45]
	s_mov_b64 s[58:59], -1
	global_store_dwordx2 v[98:99], v[86:87], off offset:256
	s_cbranch_vccnz .LBB0_890
	global_load_dwordx4 v[86:89], v[102:103], off offset:576
	s_waitcnt vmcnt(0)
	s_mov_b64 s[58:59], 0
.LBB0_890:
	s_andn2_b64 vcc, exec, s[58:59]
	s_cbranch_vccnz .LBB0_892
	s_waitcnt vmcnt(15)
	v_lshlrev_b32_e32 v86, 16, v170
	v_and_b32_e32 v87, 0xffff0000, v170
	v_lshlrev_b32_e32 v88, 16, v171
	v_and_b32_e32 v89, 0xffff0000, v171
.LBB0_892:
	v_mul_f32_e32 v102, v105, v105
	v_mul_f32_e32 v95, v95, v95
	v_fmac_f32_e32 v102, v104, v104
	v_fmac_f32_e32 v95, v94, v94
	v_mul_f32_e32 v91, v91, v91
	v_pk_add_f32 v[86:87], v[82:83], v[86:87]
	v_fmac_f32_e32 v102, v100, v100
	v_fmac_f32_e32 v95, v96, v96
	v_fmac_f32_e32 v91, v90, v90
	v_mul_f32_e32 v82, v87, v87
	v_fmac_f32_e32 v102, v101, v101
	v_fmac_f32_e32 v95, v97, v97
	v_fmac_f32_e32 v91, v92, v92
	v_pk_add_f32 v[84:85], v[84:85], v[88:89]
	v_fmac_f32_e32 v82, v86, v86
	v_add_f32_e32 v94, v102, v95
	v_fmac_f32_e32 v91, v93, v93
	v_fmac_f32_e32 v82, v84, v84
	v_add_f32_e32 v90, v94, v91
	v_fmac_f32_e32 v82, v85, v85
	v_add_f32_e32 v82, v90, v82
	ds_bpermute_b32 v83, v124, v82
	v_cvt_pk_bf16_f32 v86, v86, v87
	v_cvt_pk_bf16_f32 v87, v84, v85
	global_store_dwordx2 v[98:99], v[86:87], off offset:288
	s_waitcnt lgkmcnt(0)
	v_add_f32_e32 v82, v82, v83
	ds_bpermute_b32 v83, v125, v82
	s_and_saveexec_b64 s[58:59], s[40:41]
	s_cbranch_execz .LBB0_894
	s_waitcnt lgkmcnt(0)
	v_add_f32_e32 v84, v82, v83
	v_lshlrev_b64 v[82:83], 6, v[168:169]
	v_lshl_add_u64 v[82:83], s[92:93], 0, v[82:83]
	v_lshl_add_u64 v[82:83], s[56:57], 2, v[82:83]
	s_lshl_b32 s34, s70, 2
	v_lshl_add_u64 v[82:83], v[82:83], 0, s[34:35]
	global_store_dword v[82:83], v84, off
.LBB0_894:
	s_or_b64 exec, exec, s[58:59]
	s_waitcnt lgkmcnt(0)
	v_lshlrev_b64 v[82:83], 10, v[158:159]
	v_readlane_b32 s4, v253, 56
	v_lshl_add_u64 v[90:91], v[82:83], 0, v[154:155]
	v_readlane_b32 s5, v253, 57
	s_mov_b64 s[58:59], -1
	s_and_b64 vcc, exec, s[44:45]
	v_lshl_add_u64 v[86:87], v[90:91], 2, s[4:5]
	v_readlane_b32 s6, v253, 58
	v_readlane_b32 s7, v253, 59
	v_readlane_b32 s8, v253, 60
	v_readlane_b32 s9, v253, 61
	v_readlane_b32 s10, v253, 62
	v_readlane_b32 s11, v253, 63
	v_readlane_b32 s12, v254, 0
	v_readlane_b32 s13, v254, 1
	v_readlane_b32 s14, v254, 2
	v_readlane_b32 s15, v254, 3
	v_readlane_b32 s16, v254, 4
	v_readlane_b32 s17, v254, 5
	v_readlane_b32 s18, v254, 6
	v_readlane_b32 s19, v254, 7
	s_cbranch_vccnz .LBB0_896
	global_load_dwordx4 v[82:85], v[86:87], off
	s_waitcnt vmcnt(0)
	s_mov_b64 s[58:59], 0
.LBB0_896:
	s_andn2_b64 vcc, exec, s[58:59]
	s_cbranch_vccnz .LBB0_898
	s_waitcnt vmcnt(15)
	v_lshlrev_b32_e32 v82, 16, v166
	v_and_b32_e32 v83, 0xffff0000, v166
	v_lshlrev_b32_e32 v84, 16, v167
	v_and_b32_e32 v85, 0xffff0000, v167
.LBB0_898:
	v_pk_add_f32 v[84:85], v[80:81], v[84:85]
	v_pk_add_f32 v[88:89], v[78:79], v[82:83]
	v_cvt_pk_bf16_f32 v79, v84, v85
	v_cvt_pk_bf16_f32 v78, v88, v89
	v_lshl_add_u64 v[82:83], v[90:91], 1, s[22:23]
	s_and_b64 vcc, exec, s[44:45]
	s_mov_b64 s[58:59], -1
	global_store_dwordx2 v[82:83], v[78:79], off
	s_cbranch_vccnz .LBB0_900
	global_load_dwordx4 v[78:81], v[86:87], off offset:64
	s_waitcnt vmcnt(0)
	s_mov_b64 s[58:59], 0
.LBB0_900:
	s_andn2_b64 vcc, exec, s[58:59]
	s_cbranch_vccnz .LBB0_902
	s_waitcnt vmcnt(15)
	v_lshlrev_b32_e32 v78, 16, v164
	v_and_b32_e32 v79, 0xffff0000, v164
	v_lshlrev_b32_e32 v80, 16, v165
	v_and_b32_e32 v81, 0xffff0000, v165
.LBB0_902:
	v_pk_add_f32 v[80:81], v[76:77], v[80:81]
	v_pk_add_f32 v[78:79], v[74:75], v[78:79]
	v_cvt_pk_bf16_f32 v75, v80, v81
	v_cvt_pk_bf16_f32 v74, v78, v79
	s_and_b64 vcc, exec, s[44:45]
	s_mov_b64 s[58:59], -1
	global_store_dwordx2 v[82:83], v[74:75], off offset:32
	s_cbranch_vccnz .LBB0_904
	global_load_dwordx4 v[74:77], v[86:87], off offset:512
	s_waitcnt vmcnt(0)
	s_mov_b64 s[58:59], 0
.LBB0_904:
	s_andn2_b64 vcc, exec, s[58:59]
	s_cbranch_vccnz .LBB0_906
	s_waitcnt vmcnt(15)
	v_lshlrev_b32_e32 v74, 16, v162
	v_and_b32_e32 v75, 0xffff0000, v162
	v_lshlrev_b32_e32 v76, 16, v163
	v_and_b32_e32 v77, 0xffff0000, v163
.LBB0_906:
	v_pk_add_f32 v[76:77], v[72:73], v[76:77]
	v_pk_add_f32 v[74:75], v[70:71], v[74:75]
	v_cvt_pk_bf16_f32 v71, v76, v77
	v_cvt_pk_bf16_f32 v70, v74, v75
	s_and_b64 vcc, exec, s[44:45]
	s_mov_b64 s[58:59], -1
	global_store_dwordx2 v[82:83], v[70:71], off offset:256
	s_cbranch_vccnz .LBB0_908
	global_load_dwordx4 v[70:73], v[86:87], off offset:576
	s_waitcnt vmcnt(0)
	s_mov_b64 s[58:59], 0
.LBB0_908:
	s_andn2_b64 vcc, exec, s[58:59]
	s_cbranch_vccnz .LBB0_910
	s_waitcnt vmcnt(15)
	v_lshlrev_b32_e32 v70, 16, v160
	v_and_b32_e32 v71, 0xffff0000, v160
	v_lshlrev_b32_e32 v72, 16, v161
	v_and_b32_e32 v73, 0xffff0000, v161
.LBB0_910:
	v_mul_f32_e32 v86, v89, v89
	v_mul_f32_e32 v79, v79, v79
	v_fmac_f32_e32 v86, v88, v88
	v_fmac_f32_e32 v79, v78, v78
	v_mul_f32_e32 v75, v75, v75
	v_pk_add_f32 v[70:71], v[66:67], v[70:71]
	v_fmac_f32_e32 v86, v84, v84
	v_fmac_f32_e32 v79, v80, v80
	v_fmac_f32_e32 v75, v74, v74
	v_mul_f32_e32 v66, v71, v71
	v_fmac_f32_e32 v86, v85, v85
	v_fmac_f32_e32 v79, v81, v81
	v_fmac_f32_e32 v75, v76, v76
	v_pk_add_f32 v[68:69], v[68:69], v[72:73]
	v_fmac_f32_e32 v66, v70, v70
	v_add_f32_e32 v78, v86, v79
	v_fmac_f32_e32 v75, v77, v77
	v_fmac_f32_e32 v66, v68, v68
	v_add_f32_e32 v74, v78, v75
	v_fmac_f32_e32 v66, v69, v69
	v_add_f32_e32 v66, v74, v66
	ds_bpermute_b32 v67, v124, v66
	v_cvt_pk_bf16_f32 v70, v70, v71
	v_cvt_pk_bf16_f32 v71, v68, v69
	global_store_dwordx2 v[82:83], v[70:71], off offset:288
	s_waitcnt lgkmcnt(0)
	v_add_f32_e32 v66, v66, v67
	ds_bpermute_b32 v67, v125, v66
	s_and_saveexec_b64 s[58:59], s[40:41]
	s_cbranch_execz .LBB0_912
	s_waitcnt lgkmcnt(0)
	v_add_f32_e32 v68, v66, v67
	v_lshlrev_b64 v[66:67], 6, v[158:159]
	v_lshl_add_u64 v[66:67], s[92:93], 0, v[66:67]
	v_lshl_add_u64 v[66:67], s[56:57], 2, v[66:67]
	s_lshl_b32 s34, s70, 2
	v_lshl_add_u64 v[66:67], v[66:67], 0, s[34:35]
	global_store_dword v[66:67], v68, off

; DI unsigned pk2(float lo, float hi) { f32x2 v = {lo, hi}; bf2_t r = __builtin_convertvector(v, bf2_t); return __builtin_bit_cast(unsigned, r); }
; DI float bflo(unsigned u) { return __uint_as_float(u << 16); }
; DI float bfhi(unsigned u) { return __uint_as_float(u & 0xffff0000u); }
;   DI void operator()(const f32x4 (&acc)[2][2][4][2], const Unit& u, int wr, int wc, int fr, int fq, const PG8_LAS float* sR) const {
;     ...
; #pragma unroll
;       for (int m = 0; m < 4; ++m) {
;         const int row = row0 + ai * HALF + m * 16;
;         const size_t ro = (size_t)row * 1024 + col0;
;         float ss = 0.f;
; #pragma unroll
;         for (int bj = 0; bj < 2; ++bj)
; #pragma unroll
;           for (int n = 0; n < 2; ++n) {
;             f32x4 v;
;             if (X0 != nullptr) v = *(const f32x4*)(X0 + ro + bj * HALF + n * 16);
;             else { const u32x2 q = sv[m][bj][n]; v[0] = bflo(q[0]); v[1] = bfhi(q[0]); v[2] = bflo(q[1]); v[3] = bfhi(q[1]); }
;             v += acc[ai][bj][m][n];
;             ss += v[0] * v[0] + v[1] * v[1] + v[2] * v[2] + v[3] * v[3];
;             if (!dry) { u32x2 q; q[0] = pk2(v[0], v[1]); q[1] = pk2(v[2], v[3]); *(u32x2*)(S + ro + bj * HALF + n * 16) = q; }
;           }
;         ss += __shfl_xor(ss, 16); ss += __shfl_xor(ss, 32);
;         if (!dry && fq == 0) ssq[(size_t)row * 16 + u.pn * 4 + wc] = ss;
.LBB0_916:
	s_waitcnt lgkmcnt(0)
	v_lshlrev_b64 v[66:67], 10, v[92:93]
	v_readlane_b32 s4, v253, 56
	v_lshl_add_u64 v[106:107], v[66:67], 0, v[154:155]
	v_readlane_b32 s5, v253, 57
	s_mov_b64 s[58:59], -1
	s_and_b64 vcc, exec, s[44:45]
	v_lshl_add_u64 v[104:105], v[106:107], 2, s[4:5]
	v_readlane_b32 s6, v253, 58
	v_readlane_b32 s7, v253, 59
	v_readlane_b32 s8, v253, 60
	v_readlane_b32 s9, v253, 61
	v_readlane_b32 s10, v253, 62
	v_readlane_b32 s11, v253, 63
	v_readlane_b32 s12, v254, 0
	v_readlane_b32 s13, v254, 1
	v_readlane_b32 s14, v254, 2
	v_readlane_b32 s15, v254, 3
	v_readlane_b32 s16, v254, 4
	v_readlane_b32 s17, v254, 5
	v_readlane_b32 s18, v254, 6
	v_readlane_b32 s19, v254, 7
	s_cbranch_vccnz .LBB0_918
	global_load_dwordx4 v[66:69], v[104:105], off
	s_waitcnt vmcnt(0)
	s_mov_b64 s[58:59], 0
.LBB0_918:
	s_andn2_b64 vcc, exec, s[58:59]
	s_cbranch_vccnz .LBB0_920
	s_waitcnt vmcnt(15)
	v_lshlrev_b32_e32 v66, 16, v102
	v_and_b32_e32 v67, 0xffff0000, v102
	v_lshlrev_b32_e32 v68, 16, v103
	v_and_b32_e32 v69, 0xffff0000, v103
.LBB0_920:
	v_pk_add_f32 v[68:69], v[64:65], v[68:69]
	v_pk_add_f32 v[102:103], v[62:63], v[66:67]
	v_cvt_pk_bf16_f32 v63, v68, v69
	v_cvt_pk_bf16_f32 v62, v102, v103
	v_lshl_add_u64 v[66:67], v[106:107], 1, s[22:23]
	s_and_b64 vcc, exec, s[44:45]
	s_mov_b64 s[58:59], -1
	global_store_dwordx2 v[66:67], v[62:63], off
	s_cbranch_vccnz .LBB0_922
	global_load_dwordx4 v[62:65], v[104:105], off offset:64
	s_waitcnt vmcnt(0)
	s_mov_b64 s[58:59], 0
.LBB0_922:
	s_andn2_b64 vcc, exec, s[58:59]
	s_cbranch_vccnz .LBB0_924
	s_waitcnt vmcnt(15)
	v_lshlrev_b32_e32 v62, 16, v100
	v_and_b32_e32 v63, 0xffff0000, v100
	v_lshlrev_b32_e32 v64, 16, v101
	v_and_b32_e32 v65, 0xffff0000, v101
.LBB0_924:
	v_pk_add_f32 v[64:65], v[60:61], v[64:65]
	v_pk_add_f32 v[62:63], v[58:59], v[62:63]
	v_cvt_pk_bf16_f32 v59, v64, v65
	v_cvt_pk_bf16_f32 v58, v62, v63
	s_and_b64 vcc, exec, s[44:45]
	s_mov_b64 s[58:59], -1
	global_store_dwordx2 v[66:67], v[58:59], off offset:32
	s_cbranch_vccnz .LBB0_926
	global_load_dwordx4 v[58:61], v[104:105], off offset:512
	s_waitcnt vmcnt(0)
	s_mov_b64 s[58:59], 0
.LBB0_926:
	s_andn2_b64 vcc, exec, s[58:59]
	s_cbranch_vccnz .LBB0_928
	s_waitcnt vmcnt(15)
	v_lshlrev_b32_e32 v58, 16, v98
	v_and_b32_e32 v59, 0xffff0000, v98
	v_lshlrev_b32_e32 v60, 16, v99
	v_and_b32_e32 v61, 0xffff0000, v99
.LBB0_928:
	v_pk_add_f32 v[60:61], v[56:57], v[60:61]
	v_pk_add_f32 v[58:59], v[54:55], v[58:59]
	v_cvt_pk_bf16_f32 v55, v60, v61
	v_cvt_pk_bf16_f32 v54, v58, v59
	s_and_b64 vcc, exec, s[44:45]
	s_mov_b64 s[58:59], -1
	global_store_dwordx2 v[66:67], v[54:55], off offset:256
	s_cbranch_vccnz .LBB0_930
	global_load_dwordx4 v[54:57], v[104:105], off offset:576
	s_waitcnt vmcnt(0)
	s_mov_b64 s[58:59], 0
.LBB0_930:
	s_andn2_b64 vcc, exec, s[58:59]
	s_cbranch_vccnz .LBB0_932
	s_waitcnt vmcnt(15)
	v_lshlrev_b32_e32 v54, 16, v96
	v_and_b32_e32 v55, 0xffff0000, v96
	v_lshlrev_b32_e32 v56, 16, v97
	v_and_b32_e32 v57, 0xffff0000, v97
.LBB0_932:
	v_mul_f32_e32 v96, v103, v103
	v_mul_f32_e32 v63, v63, v63
	v_fmac_f32_e32 v96, v102, v102
	v_fmac_f32_e32 v63, v62, v62
	v_mul_f32_e32 v59, v59, v59
	v_pk_add_f32 v[54:55], v[50:51], v[54:55]
	v_fmac_f32_e32 v96, v68, v68
	v_fmac_f32_e32 v63, v64, v64
	v_fmac_f32_e32 v59, v58, v58
	v_mul_f32_e32 v50, v55, v55
	v_fmac_f32_e32 v96, v69, v69
	v_fmac_f32_e32 v63, v65, v65
	v_fmac_f32_e32 v59, v60, v60
	v_pk_add_f32 v[52:53], v[52:53], v[56:57]
	v_fmac_f32_e32 v50, v54, v54
	v_add_f32_e32 v62, v96, v63
	v_fmac_f32_e32 v59, v61, v61
	v_fmac_f32_e32 v50, v52, v52
	v_add_f32_e32 v58, v62, v59
	v_fmac_f32_e32 v50, v53, v53
	v_add_f32_e32 v50, v58, v50
	ds_bpermute_b32 v51, v124, v50
	v_cvt_pk_bf16_f32 v54, v54, v55
	v_cvt_pk_bf16_f32 v55, v52, v53
	global_store_dwordx2 v[66:67], v[54:55], off offset:288
	s_waitcnt lgkmcnt(0)
	v_add_f32_e32 v50, v50, v51
	ds_bpermute_b32 v51, v125, v50
	s_and_saveexec_b64 s[58:59], s[40:41]
	s_cbranch_execz .LBB0_934
	s_waitcnt lgkmcnt(0)
	v_add_f32_e32 v52, v50, v51
	v_lshlrev_b64 v[50:51], 6, v[92:93]
	v_lshl_add_u64 v[50:51], s[92:93], 0, v[50:51]
	v_lshl_add_u64 v[50:51], s[56:57], 2, v[50:51]
	s_lshl_b32 s34, s70, 2
	v_lshl_add_u64 v[50:51], v[50:51], 0, s[34:35]
	global_store_dword v[50:51], v52, off
.LBB0_934:
	s_or_b64 exec, exec, s[58:59]
	v_add_u32_e32 v54, 0x90, v152
	v_ashrrev_i32_e32 v55, 31, v54
	s_waitcnt lgkmcnt(0)
	v_lshlrev_b64 v[50:51], 10, v[54:55]
	v_readlane_b32 s4, v253, 56
	v_lshl_add_u64 v[60:61], v[50:51], 0, v[154:155]
	v_readlane_b32 s5, v253, 57
	s_mov_b64 s[58:59], -1
	s_and_b64 vcc, exec, s[44:45]
	v_lshl_add_u64 v[56:57], v[60:61], 2, s[4:5]
	v_readlane_b32 s6, v253, 58
	v_readlane_b32 s7, v253, 59
	v_readlane_b32 s8, v253, 60
	v_readlane_b32 s9, v253, 61
	v_readlane_b32 s10, v253, 62
	v_readlane_b32 s11, v253, 63
	v_readlane_b32 s12, v254, 0
	v_readlane_b32 s13, v254, 1
	v_readlane_b32 s14, v254, 2
	v_readlane_b32 s15, v254, 3
	v_readlane_b32 s16, v254, 4
	v_readlane_b32 s17, v254, 5
	v_readlane_b32 s18, v254, 6
	v_readlane_b32 s19, v254, 7
	s_cbranch_vccnz .LBB0_936
	global_load_dwordx4 v[50:53], v[56:57], off
	s_waitcnt vmcnt(0)
	s_mov_b64 s[58:59], 0
.LBB0_936:
	s_andn2_b64 vcc, exec, s[58:59]
	s_cbranch_vccnz .LBB0_938
	s_waitcnt vmcnt(15)
	v_lshlrev_b32_e32 v50, 16, v94
	v_and_b32_e32 v51, 0xffff0000, v94
	v_lshlrev_b32_e32 v52, 16, v95
	v_and_b32_e32 v53, 0xffff0000, v95
.LBB0_938:
	v_pk_add_f32 v[52:53], v[48:49], v[52:53]
	v_pk_add_f32 v[58:59], v[46:47], v[50:51]
	v_cvt_pk_bf16_f32 v47, v52, v53
	v_cvt_pk_bf16_f32 v46, v58, v59
	v_lshl_add_u64 v[50:51], v[60:61], 1, s[22:23]
	s_and_b64 vcc, exec, s[44:45]
	s_mov_b64 s[58:59], -1
	global_store_dwordx2 v[50:51], v[46:47], off
	s_cbranch_vccnz .LBB0_940
	global_load_dwordx4 v[46:49], v[56:57], off offset:64
	s_waitcnt vmcnt(0)
	s_mov_b64 s[58:59], 0
; DI unsigned pk2(float lo, float hi) { f32x2 v = {lo, hi}; bf2_t r = __builtin_convertvector(v, bf2_t); return __builtin_bit_cast(unsigned, r); }
; DI float bflo(unsigned u) { return __uint_as_float(u << 16); }
; DI float bfhi(unsigned u) { return __uint_as_float(u & 0xffff0000u); }
;   DI void operator()(const f32x4 (&acc)[2][2][4][2], const Unit& u, int wr, int wc, int fr, int fq, const PG8_LAS float* sR) const {
;     ...
; #pragma unroll
;       for (int m = 0; m < 4; ++m) {
;         const int row = row0 + ai * HALF + m * 16;
;         const size_t ro = (size_t)row * 1024 + col0;
;         float ss = 0.f;
; #pragma unroll
;         for (int bj = 0; bj < 2; ++bj)
; #pragma unroll
;           for (int n = 0; n < 2; ++n) {
;             f32x4 v;
;             if (X0 != nullptr) v = *(const f32x4*)(X0 + ro + bj * HALF + n * 16);
;             else { const u32x2 q = sv[m][bj][n]; v[0] = bflo(q[0]); v[1] = bfhi(q[0]); v[2] = bflo(q[1]); v[3] = bfhi(q[1]); }
;             v += acc[ai][bj][m][n];
;             ss += v[0] * v[0] + v[1] * v[1] + v[2] * v[2] + v[3] * v[3];
;             if (!dry) { u32x2 q; q[0] = pk2(v[0], v[1]); q[1] = pk2(v[2], v[3]); *(u32x2*)(S + ro + bj * HALF + n * 16) = q; }
;           }
;         ss += __shfl_xor(ss, 16); ss += __shfl_xor(ss, 32);
;         if (!dry && fq == 0) ssq[(size_t)row * 16 + u.pn * 4 + wc] = ss;
.LBB0_940:
	s_andn2_b64 vcc, exec, s[58:59]
	s_cbranch_vccnz .LBB0_942
	s_waitcnt vmcnt(15)
	v_lshlrev_b32_e32 v46, 16, v90
	v_and_b32_e32 v47, 0xffff0000, v90
	v_lshlrev_b32_e32 v48, 16, v91
	v_and_b32_e32 v49, 0xffff0000, v91
.LBB0_942:
	v_pk_add_f32 v[48:49], v[44:45], v[48:49]
	v_pk_add_f32 v[46:47], v[42:43], v[46:47]
	v_cvt_pk_bf16_f32 v43, v48, v49
	v_cvt_pk_bf16_f32 v42, v46, v47
	s_and_b64 vcc, exec, s[44:45]
	s_mov_b64 s[58:59], -1
	global_store_dwordx2 v[50:51], v[42:43], off offset:32
	s_cbranch_vccnz .LBB0_944
	global_load_dwordx4 v[42:45], v[56:57], off offset:512
	s_waitcnt vmcnt(0)
	s_mov_b64 s[58:59], 0
.LBB0_944:
	s_andn2_b64 vcc, exec, s[58:59]
	s_cbranch_vccnz .LBB0_946
	s_waitcnt vmcnt(15)
	v_lshlrev_b32_e32 v42, 16, v88
	v_and_b32_e32 v43, 0xffff0000, v88
	v_lshlrev_b32_e32 v44, 16, v89
	v_and_b32_e32 v45, 0xffff0000, v89
.LBB0_946:
	v_pk_add_f32 v[44:45], v[40:41], v[44:45]
	v_pk_add_f32 v[42:43], v[38:39], v[42:43]
	v_cvt_pk_bf16_f32 v39, v44, v45
	v_cvt_pk_bf16_f32 v38, v42, v43
	s_and_b64 vcc, exec, s[44:45]
	s_mov_b64 s[58:59], -1
	global_store_dwordx2 v[50:51], v[38:39], off offset:256
	s_cbranch_vccnz .LBB0_948
	global_load_dwordx4 v[38:41], v[56:57], off offset:576
	s_waitcnt vmcnt(0)
	s_mov_b64 s[58:59], 0
.LBB0_948:
	s_andn2_b64 vcc, exec, s[58:59]
	s_cbranch_vccnz .LBB0_950
	s_waitcnt vmcnt(15)
	v_lshlrev_b32_e32 v38, 16, v86
	v_and_b32_e32 v39, 0xffff0000, v86
	v_lshlrev_b32_e32 v40, 16, v87
	v_and_b32_e32 v41, 0xffff0000, v87
.LBB0_950:
	v_mul_f32_e32 v56, v59, v59
	v_mul_f32_e32 v47, v47, v47
	v_fmac_f32_e32 v56, v58, v58
	v_fmac_f32_e32 v47, v46, v46
	v_mul_f32_e32 v43, v43, v43
	v_pk_add_f32 v[38:39], v[34:35], v[38:39]
	v_fmac_f32_e32 v56, v52, v52
	v_fmac_f32_e32 v47, v48, v48
	v_fmac_f32_e32 v43, v42, v42
	v_mul_f32_e32 v34, v39, v39
	v_fmac_f32_e32 v56, v53, v53
	v_fmac_f32_e32 v47, v49, v49
	v_fmac_f32_e32 v43, v44, v44
	v_pk_add_f32 v[36:37], v[36:37], v[40:41]
	v_fmac_f32_e32 v34, v38, v38
	v_add_f32_e32 v46, v56, v47
	v_fmac_f32_e32 v43, v45, v45
	v_fmac_f32_e32 v34, v36, v36
	v_add_f32_e32 v42, v46, v43
	v_fmac_f32_e32 v34, v37, v37
	v_add_f32_e32 v34, v42, v34
	ds_bpermute_b32 v35, v124, v34
	v_cvt_pk_bf16_f32 v38, v38, v39
	v_cvt_pk_bf16_f32 v39, v36, v37
	global_store_dwordx2 v[50:51], v[38:39], off offset:288
	s_waitcnt lgkmcnt(0)
	v_add_f32_e32 v34, v34, v35
	ds_bpermute_b32 v35, v125, v34
	s_and_saveexec_b64 s[58:59], s[40:41]
	s_cbranch_execz .LBB0_952
	s_waitcnt lgkmcnt(0)
	v_add_f32_e32 v36, v34, v35
	v_lshlrev_b64 v[34:35], 6, v[54:55]
	v_lshl_add_u64 v[34:35], s[92:93], 0, v[34:35]
	v_lshl_add_u64 v[34:35], s[56:57], 2, v[34:35]
	s_lshl_b32 s34, s70, 2
	v_lshl_add_u64 v[34:35], v[34:35], 0, s[34:35]
	global_store_dword v[34:35], v36, off
.LBB0_952:
	s_or_b64 exec, exec, s[58:59]
	v_add_u32_e32 v38, 0xa0, v152
	v_ashrrev_i32_e32 v39, 31, v38
	s_waitcnt lgkmcnt(0)
	v_lshlrev_b64 v[34:35], 10, v[38:39]
	v_readlane_b32 s4, v253, 56
	v_lshl_add_u64 v[44:45], v[34:35], 0, v[154:155]
	v_readlane_b32 s5, v253, 57
	s_mov_b64 s[58:59], -1
	s_and_b64 vcc, exec, s[44:45]
	v_lshl_add_u64 v[40:41], v[44:45], 2, s[4:5]
	v_readlane_b32 s6, v253, 58
	v_readlane_b32 s7, v253, 59
	v_readlane_b32 s8, v253, 60
	v_readlane_b32 s9, v253, 61
	v_readlane_b32 s10, v253, 62
	v_readlane_b32 s11, v253, 63
	v_readlane_b32 s12, v254, 0
	v_readlane_b32 s13, v254, 1
	v_readlane_b32 s14, v254, 2
	v_readlane_b32 s15, v254, 3
	v_readlane_b32 s16, v254, 4
	v_readlane_b32 s17, v254, 5
	v_readlane_b32 s18, v254, 6
	v_readlane_b32 s19, v254, 7
	s_cbranch_vccnz .LBB0_954
	global_load_dwordx4 v[34:37], v[40:41], off
	s_waitcnt vmcnt(0)
	s_mov_b64 s[58:59], 0
.LBB0_954:
	s_andn2_b64 vcc, exec, s[58:59]
	s_cbranch_vccnz .LBB0_956
	s_waitcnt vmcnt(15)
	v_lshlrev_b32_e32 v34, 16, v84
	v_and_b32_e32 v35, 0xffff0000, v84
	v_lshlrev_b32_e32 v36, 16, v85
	v_and_b32_e32 v37, 0xffff0000, v85
.LBB0_956:
	v_pk_add_f32 v[36:37], v[32:33], v[36:37]
	v_pk_add_f32 v[42:43], v[30:31], v[34:35]
	v_cvt_pk_bf16_f32 v31, v36, v37
	v_cvt_pk_bf16_f32 v30, v42, v43
	v_lshl_add_u64 v[34:35], v[44:45], 1, s[22:23]
	s_and_b64 vcc, exec, s[44:45]
	s_mov_b64 s[58:59], -1
	global_store_dwordx2 v[34:35], v[30:31], off
	s_cbranch_vccnz .LBB0_958
	global_load_dwordx4 v[30:33], v[40:41], off offset:64
	s_waitcnt vmcnt(0)
	s_mov_b64 s[58:59], 0
.LBB0_958:
	s_andn2_b64 vcc, exec, s[58:59]
	s_cbranch_vccnz .LBB0_960
	s_waitcnt vmcnt(15)
	v_lshlrev_b32_e32 v30, 16, v82
	v_and_b32_e32 v31, 0xffff0000, v82
	v_lshlrev_b32_e32 v32, 16, v83
	v_and_b32_e32 v33, 0xffff0000, v83
.LBB0_960:
	v_pk_add_f32 v[32:33], v[28:29], v[32:33]
	v_pk_add_f32 v[30:31], v[26:27], v[30:31]
	v_cvt_pk_bf16_f32 v27, v32, v33
	v_cvt_pk_bf16_f32 v26, v30, v31
	s_and_b64 vcc, exec, s[44:45]
	s_mov_b64 s[58:59], -1
	global_store_dwordx2 v[34:35], v[26:27], off offset:32
	s_cbranch_vccnz .LBB0_962
	global_load_dwordx4 v[26:29], v[40:41], off offset:512
	s_waitcnt vmcnt(0)
	s_mov_b64 s[58:59], 0
.LBB0_962:
	s_andn2_b64 vcc, exec, s[58:59]
	s_cbranch_vccnz .LBB0_964
	s_waitcnt vmcnt(15)
	v_lshlrev_b32_e32 v26, 16, v80
	v_and_b32_e32 v27, 0xffff0000, v80
	v_lshlrev_b32_e32 v28, 16, v81
	v_and_b32_e32 v29, 0xffff0000, v81
.LBB0_964:
	v_pk_add_f32 v[28:29], v[24:25], v[28:29]
	v_pk_add_f32 v[26:27], v[22:23], v[26:27]
	v_cvt_pk_bf16_f32 v23, v28, v29
	v_cvt_pk_bf16_f32 v22, v26, v27
	s_and_b64 vcc, exec, s[44:45]
	s_mov_b64 s[58:59], -1
	global_store_dwordx2 v[34:35], v[22:23], off offset:256
	s_cbranch_vccnz .LBB0_966
	global_load_dwordx4 v[22:25], v[40:41], off offset:576
	s_waitcnt vmcnt(0)
	s_mov_b64 s[58:59], 0
; DI unsigned pk2(float lo, float hi) { f32x2 v = {lo, hi}; bf2_t r = __builtin_convertvector(v, bf2_t); return __builtin_bit_cast(unsigned, r); }
; DI float bflo(unsigned u) { return __uint_as_float(u << 16); }
; DI float bfhi(unsigned u) { return __uint_as_float(u & 0xffff0000u); }
;   DI void operator()(const f32x4 (&acc)[2][2][4][2], const Unit& u, int wr, int wc, int fr, int fq, const PG8_LAS float* sR) const {
;     ...
; #pragma unroll
;       for (int m = 0; m < 4; ++m) {
;         const int row = row0 + ai * HALF + m * 16;
;         const size_t ro = (size_t)row * 1024 + col0;
;         float ss = 0.f;
; #pragma unroll
;         for (int bj = 0; bj < 2; ++bj)
; #pragma unroll
;           for (int n = 0; n < 2; ++n) {
;             f32x4 v;
;             if (X0 != nullptr) v = *(const f32x4*)(X0 + ro + bj * HALF + n * 16);
;             else { const u32x2 q = sv[m][bj][n]; v[0] = bflo(q[0]); v[1] = bfhi(q[0]); v[2] = bflo(q[1]); v[3] = bfhi(q[1]); }
;             v += acc[ai][bj][m][n];
;             ss += v[0] * v[0] + v[1] * v[1] + v[2] * v[2] + v[3] * v[3];
;             if (!dry) { u32x2 q; q[0] = pk2(v[0], v[1]); q[1] = pk2(v[2], v[3]); *(u32x2*)(S + ro + bj * HALF + n * 16) = q; }
;           }
;         ss += __shfl_xor(ss, 16); ss += __shfl_xor(ss, 32);
;         if (!dry && fq == 0) ssq[(size_t)row * 16 + u.pn * 4 + wc] = ss;
;       }
.LBB0_966:
	s_andn2_b64 vcc, exec, s[58:59]
	s_cbranch_vccnz .LBB0_968
	s_waitcnt vmcnt(15)
	v_lshlrev_b32_e32 v22, 16, v78
	v_and_b32_e32 v23, 0xffff0000, v78
	v_lshlrev_b32_e32 v24, 16, v79
	v_and_b32_e32 v25, 0xffff0000, v79
.LBB0_968:
	v_mul_f32_e32 v40, v43, v43
	v_mul_f32_e32 v31, v31, v31
	v_fmac_f32_e32 v40, v42, v42
	v_fmac_f32_e32 v31, v30, v30
	v_mul_f32_e32 v27, v27, v27
	v_pk_add_f32 v[22:23], v[18:19], v[22:23]
	v_fmac_f32_e32 v40, v36, v36
	v_fmac_f32_e32 v31, v32, v32
	v_fmac_f32_e32 v27, v26, v26
	v_mul_f32_e32 v18, v23, v23
	v_fmac_f32_e32 v40, v37, v37
	v_fmac_f32_e32 v31, v33, v33
	v_fmac_f32_e32 v27, v28, v28
	v_pk_add_f32 v[20:21], v[20:21], v[24:25]
	v_fmac_f32_e32 v18, v22, v22
	v_add_f32_e32 v30, v40, v31
	v_fmac_f32_e32 v27, v29, v29
	v_fmac_f32_e32 v18, v20, v20
	v_add_f32_e32 v26, v30, v27
	v_fmac_f32_e32 v18, v21, v21
	v_add_f32_e32 v18, v26, v18
	ds_bpermute_b32 v19, v124, v18
	v_cvt_pk_bf16_f32 v22, v22, v23
	v_cvt_pk_bf16_f32 v23, v20, v21
	global_store_dwordx2 v[34:35], v[22:23], off offset:288
	s_waitcnt lgkmcnt(0)
	v_add_f32_e32 v18, v18, v19
	ds_bpermute_b32 v19, v125, v18
	s_and_saveexec_b64 s[58:59], s[40:41]
	s_cbranch_execz .LBB0_970
	s_waitcnt lgkmcnt(0)
	v_add_f32_e32 v20, v18, v19
	v_lshlrev_b64 v[18:19], 6, v[38:39]
	v_lshl_add_u64 v[18:19], s[92:93], 0, v[18:19]
	v_lshl_add_u64 v[18:19], s[56:57], 2, v[18:19]
	s_lshl_b32 s34, s70, 2
	v_lshl_add_u64 v[18:19], v[18:19], 0, s[34:35]
	global_store_dword v[18:19], v20, off
.LBB0_970:
	s_or_b64 exec, exec, s[58:59]
	v_add_u32_e32 v22, 0xb0, v152
	v_ashrrev_i32_e32 v23, 31, v22
	s_waitcnt lgkmcnt(0)
	v_lshlrev_b64 v[18:19], 10, v[22:23]
	v_readlane_b32 s4, v253, 56
	v_lshl_add_u64 v[28:29], v[18:19], 0, v[154:155]
	v_readlane_b32 s5, v253, 57
	s_mov_b64 s[58:59], -1
	s_and_b64 vcc, exec, s[44:45]
	v_lshl_add_u64 v[24:25], v[28:29], 2, s[4:5]
	v_readlane_b32 s6, v253, 58
	v_readlane_b32 s7, v253, 59
	v_readlane_b32 s8, v253, 60
	v_readlane_b32 s9, v253, 61
	v_readlane_b32 s10, v253, 62
	v_readlane_b32 s11, v253, 63
	v_readlane_b32 s12, v254, 0
	v_readlane_b32 s13, v254, 1
	v_readlane_b32 s14, v254, 2
	v_readlane_b32 s15, v254, 3
	v_readlane_b32 s16, v254, 4
	v_readlane_b32 s17, v254, 5
	v_readlane_b32 s18, v254, 6
	v_readlane_b32 s19, v254, 7
	s_cbranch_vccnz .LBB0_972
	global_load_dwordx4 v[18:21], v[24:25], off
	s_waitcnt vmcnt(0)
	s_mov_b64 s[58:59], 0
.LBB0_972:
	s_andn2_b64 vcc, exec, s[58:59]
	s_cbranch_vccnz .LBB0_974
	s_waitcnt vmcnt(15)
	v_lshlrev_b32_e32 v18, 16, v76
	v_and_b32_e32 v19, 0xffff0000, v76
	v_lshlrev_b32_e32 v20, 16, v77
	v_and_b32_e32 v21, 0xffff0000, v77
.LBB0_974:
	v_pk_add_f32 v[20:21], v[16:17], v[20:21]
	v_pk_add_f32 v[26:27], v[14:15], v[18:19]
	v_cvt_pk_bf16_f32 v15, v20, v21
	v_cvt_pk_bf16_f32 v14, v26, v27
	v_lshl_add_u64 v[18:19], v[28:29], 1, s[22:23]
	s_and_b64 vcc, exec, s[44:45]
	s_mov_b64 s[58:59], -1
	global_store_dwordx2 v[18:19], v[14:15], off
	s_cbranch_vccnz .LBB0_976
	global_load_dwordx4 v[14:17], v[24:25], off offset:64
	s_waitcnt vmcnt(0)
	s_mov_b64 s[58:59], 0
.LBB0_976:
	s_andn2_b64 vcc, exec, s[58:59]
	s_cbranch_vccnz .LBB0_978
	s_waitcnt vmcnt(15)
	v_lshlrev_b32_e32 v14, 16, v74
	v_and_b32_e32 v15, 0xffff0000, v74
	v_lshlrev_b32_e32 v16, 16, v75
	v_and_b32_e32 v17, 0xffff0000, v75
.LBB0_978:
	v_pk_add_f32 v[16:17], v[12:13], v[16:17]
	v_pk_add_f32 v[14:15], v[10:11], v[14:15]
	v_cvt_pk_bf16_f32 v11, v16, v17
	v_cvt_pk_bf16_f32 v10, v14, v15
	s_and_b64 vcc, exec, s[44:45]
	s_mov_b64 s[58:59], -1
	global_store_dwordx2 v[18:19], v[10:11], off offset:32
	s_cbranch_vccnz .LBB0_980
	global_load_dwordx4 v[10:13], v[24:25], off offset:512
	s_waitcnt vmcnt(0)
	s_mov_b64 s[58:59], 0
.LBB0_980:
	s_andn2_b64 vcc, exec, s[58:59]
	s_cbranch_vccnz .LBB0_982
	s_waitcnt vmcnt(15)
	v_lshlrev_b32_e32 v10, 16, v72
	v_and_b32_e32 v11, 0xffff0000, v72
	v_lshlrev_b32_e32 v12, 16, v73
	v_and_b32_e32 v13, 0xffff0000, v73
.LBB0_982:
	v_pk_add_f32 v[12:13], v[8:9], v[12:13]
	v_pk_add_f32 v[10:11], v[6:7], v[10:11]
	v_cvt_pk_bf16_f32 v7, v12, v13
	v_cvt_pk_bf16_f32 v6, v10, v11
	s_and_b64 vcc, exec, s[44:45]
	s_mov_b64 s[44:45], -1
	global_store_dwordx2 v[18:19], v[6:7], off offset:256
	s_cbranch_vccnz .LBB0_984
	global_load_dwordx4 v[6:9], v[24:25], off offset:576
	s_waitcnt vmcnt(0)
	s_mov_b64 s[44:45], 0
.LBB0_984:
	s_andn2_b64 vcc, exec, s[44:45]
	s_cbranch_vccnz .LBB0_986
	s_waitcnt vmcnt(15)
	v_lshlrev_b32_e32 v6, 16, v70
	v_and_b32_e32 v7, 0xffff0000, v70
	v_lshlrev_b32_e32 v8, 16, v71
	v_and_b32_e32 v9, 0xffff0000, v71
.LBB0_986:
	v_mul_f32_e32 v24, v27, v27
	v_mul_f32_e32 v15, v15, v15
	v_fmac_f32_e32 v24, v26, v26
	v_fmac_f32_e32 v15, v14, v14
	v_mul_f32_e32 v11, v11, v11
	v_pk_add_f32 v[6:7], v[2:3], v[6:7]
	v_fmac_f32_e32 v24, v20, v20
	v_fmac_f32_e32 v15, v16, v16
	v_fmac_f32_e32 v11, v10, v10
	v_mul_f32_e32 v2, v7, v7
	v_fmac_f32_e32 v24, v21, v21
	v_fmac_f32_e32 v15, v17, v17
	v_fmac_f32_e32 v11, v12, v12
	v_pk_add_f32 v[4:5], v[4:5], v[8:9]
	v_fmac_f32_e32 v2, v6, v6
	v_add_f32_e32 v14, v24, v15
	v_fmac_f32_e32 v11, v13, v13
	v_fmac_f32_e32 v2, v4, v4
	v_add_f32_e32 v10, v14, v11
	v_fmac_f32_e32 v2, v5, v5
	v_add_f32_e32 v2, v10, v2
	ds_bpermute_b32 v3, v124, v2
	v_cvt_pk_bf16_f32 v6, v6, v7
	v_cvt_pk_bf16_f32 v7, v4, v5
	global_store_dwordx2 v[18:19], v[6:7], off offset:288
	s_waitcnt lgkmcnt(0)
	v_add_f32_e32 v2, v2, v3
	ds_bpermute_b32 v3, v125, v2
	s_and_saveexec_b64 s[44:45], s[40:41]
	s_cbranch_execz .LBB0_823
	s_waitcnt lgkmcnt(0)
	v_add_f32_e32 v4, v2, v3
	v_lshlrev_b64 v[2:3], 6, v[22:23]
	v_lshl_add_u64 v[2:3], s[92:93], 0, v[2:3]
	v_lshl_add_u64 v[2:3], s[56:57], 2, v[2:3]
	s_lshl_b32 s34, s70, 2
	v_lshl_add_u64 v[2:3], v[2:3], 0, s[34:35]
	global_store_dword v[2:3], v4, off
	s_branch .LBB0_823
